# previous + all non-nt P1 in-proj epilogue stores (Z, GC, UPP/UPS, conv outputs) written through (sc0 sc1) to shorten the seam-1 barrier L2 write-back
# speedup vs baseline: 1.0190x; 1.0190x over previous
.LBB0_180:
	ds_read_b128 v[130:133], v185
	ds_read_b128 v[134:137], v185 offset:1024
	ds_read_b128 v[138:141], v185 offset:2048
	ds_read_b128 v[174:177], v185 offset:3072
	s_add_u32 s0, s12, 0xfff80080
	s_addc_u32 s1, s13, -1
	s_cmp_eq_u32 s38, 28
	s_cselect_b32 s3, s9, s1
	s_cselect_b32 s2, s11, s0
	s_cselect_b32 s1, s14, s37
	s_cselect_b32 s0, s15, s36
	v_lshl_add_u64 v[182:183], s[12:13], 0, v[162:163]
	s_add_i32 m0, s30, 0xc000
	ds_read_b128 v[178:181], v186
	ds_read_b128 v[190:193], v186 offset:1024
	ds_read_b128 v[196:199], v186 offset:2048
	ds_read_b128 v[200:203], v186 offset:3072
	ds_read_b128 v[204:207], v186 offset:4096
	ds_read_b128 v[208:211], v186 offset:5120
	ds_read_b128 v[212:215], v186 offset:6144
	ds_read_b128 v[216:219], v186 offset:7168
	global_load_lds_dwordx4 v[182:183], off
	v_lshl_add_u64 v[182:183], s[12:13], 0, v[164:165]
	s_add_i32 m0, s30, 0xe000
	s_nop 0
	global_load_lds_dwordx4 v[182:183], off
	s_waitcnt lgkmcnt(8)
	s_barrier
	s_waitcnt lgkmcnt(0)
	s_setprio 1
	s_waitcnt lgkmcnt(0)
	v_mfma_f32_16x16x32_bf16 v[122:125], v[130:133], v[178:181], v[122:125]
	v_mfma_f32_16x16x32_bf16 v[126:129], v[138:141], v[178:181], v[126:129]
	v_mfma_f32_16x16x32_bf16 v[106:109], v[130:133], v[196:199], v[106:109]
	v_mfma_f32_16x16x32_bf16 v[110:113], v[138:141], v[196:199], v[110:113]
	v_mfma_f32_16x16x32_bf16 v[90:93], v[130:133], v[204:207], v[90:93]
	v_mfma_f32_16x16x32_bf16 v[94:97], v[138:141], v[204:207], v[94:97]
	v_mfma_f32_16x16x32_bf16 v[74:77], v[130:133], v[212:215], v[74:77]
	v_mfma_f32_16x16x32_bf16 v[78:81], v[138:141], v[212:215], v[78:81]
	v_mfma_f32_16x16x32_bf16 v[122:125], v[134:137], v[190:193], v[122:125]
	v_mfma_f32_16x16x32_bf16 v[126:129], v[174:177], v[190:193], v[126:129]
	v_mfma_f32_16x16x32_bf16 v[106:109], v[134:137], v[200:203], v[106:109]
	v_mfma_f32_16x16x32_bf16 v[110:113], v[174:177], v[200:203], v[110:113]
	v_mfma_f32_16x16x32_bf16 v[90:93], v[134:137], v[208:211], v[90:93]
	v_mfma_f32_16x16x32_bf16 v[94:97], v[174:177], v[208:211], v[94:97]
	v_mfma_f32_16x16x32_bf16 v[74:77], v[134:137], v[216:219], v[74:77]
	v_mfma_f32_16x16x32_bf16 v[78:81], v[174:177], v[216:219], v[78:81]
	s_setprio 0
	s_barrier
	s_add_i32 s39, s84, s23
	v_lshl_add_u64 v[182:183], s[0:1], 0, v[146:147]
	s_mov_b32 m0, s39
	ds_read_b128 v[220:223], v187
	ds_read_b128 v[224:227], v187 offset:1024
	ds_read_b128 v[228:231], v187 offset:2048
	ds_read_b128 v[232:235], v187 offset:3072
	global_load_lds_dwordx4 v[182:183], off
	v_lshl_add_u64 v[236:237], s[0:1], 0, v[150:151]
	s_add_i32 m0, s39, 0x2000
	s_nop 0
	global_load_lds_dwordx4 v[236:237], off
	s_barrier
	s_waitcnt lgkmcnt(0)
	s_setprio 1
	s_waitcnt lgkmcnt(0)
	v_mfma_f32_16x16x32_bf16 v[114:117], v[220:223], v[178:181], v[114:117]
	v_mfma_f32_16x16x32_bf16 v[118:121], v[228:231], v[178:181], v[118:121]
	v_mfma_f32_16x16x32_bf16 v[98:101], v[220:223], v[196:199], v[98:101]
	v_mfma_f32_16x16x32_bf16 v[102:105], v[228:231], v[196:199], v[102:105]
	v_mfma_f32_16x16x32_bf16 v[82:85], v[220:223], v[204:207], v[82:85]
	v_mfma_f32_16x16x32_bf16 v[86:89], v[228:231], v[204:207], v[86:89]
	v_mfma_f32_16x16x32_bf16 v[66:69], v[220:223], v[212:215], v[66:69]
	v_mfma_f32_16x16x32_bf16 v[70:73], v[228:231], v[212:215], v[70:73]
	v_mfma_f32_16x16x32_bf16 v[114:117], v[224:227], v[190:193], v[114:117]
	v_mfma_f32_16x16x32_bf16 v[118:121], v[232:235], v[190:193], v[118:121]
	v_mfma_f32_16x16x32_bf16 v[98:101], v[224:227], v[200:203], v[98:101]
	v_mfma_f32_16x16x32_bf16 v[102:105], v[232:235], v[200:203], v[102:105]
	v_mfma_f32_16x16x32_bf16 v[82:85], v[224:227], v[208:211], v[82:85]
	v_mfma_f32_16x16x32_bf16 v[86:89], v[232:235], v[208:211], v[86:89]
	v_mfma_f32_16x16x32_bf16 v[66:69], v[224:227], v[216:219], v[66:69]
	v_mfma_f32_16x16x32_bf16 v[70:73], v[232:235], v[216:219], v[70:73]
	s_setprio 0
	s_mov_b32 m0, s30
	v_lshl_add_u64 v[238:239], s[2:3], 0, v[144:145]
	s_barrier
	ds_read_b128 v[178:181], v186 offset:16384
	ds_read_b128 v[190:193], v186 offset:17408
	ds_read_b128 v[196:199], v186 offset:18432
	ds_read_b128 v[200:203], v186 offset:19456
	ds_read_b128 v[204:207], v186 offset:20480
	ds_read_b128 v[208:211], v186 offset:21504
	ds_read_b128 v[212:215], v186 offset:22528
	ds_read_b128 v[216:219], v186 offset:23552
	global_load_lds_dwordx4 v[238:239], off
	v_lshl_add_u64 v[240:241], s[2:3], 0, v[148:149]
	s_mov_b32 m0, s31
	s_nop 0
	global_load_lds_dwordx4 v[240:241], off
	s_barrier
	s_waitcnt lgkmcnt(0)
	s_setprio 1
	s_waitcnt lgkmcnt(0)
	v_mfma_f32_16x16x32_bf16 v[58:61], v[130:133], v[178:181], v[58:61]
	v_mfma_f32_16x16x32_bf16 v[62:65], v[138:141], v[178:181], v[62:65]
	v_mfma_f32_16x16x32_bf16 v[42:45], v[130:133], v[196:199], v[42:45]
	v_mfma_f32_16x16x32_bf16 v[46:49], v[138:141], v[196:199], v[46:49]
	v_mfma_f32_16x16x32_bf16 v[26:29], v[130:133], v[204:207], v[26:29]
	v_mfma_f32_16x16x32_bf16 v[30:33], v[138:141], v[204:207], v[30:33]
	v_mfma_f32_16x16x32_bf16 v[10:13], v[130:133], v[212:215], v[10:13]
	v_mfma_f32_16x16x32_bf16 v[14:17], v[138:141], v[212:215], v[14:17]
	v_mfma_f32_16x16x32_bf16 v[58:61], v[134:137], v[190:193], v[58:61]
	v_mfma_f32_16x16x32_bf16 v[62:65], v[174:177], v[190:193], v[62:65]
	v_mfma_f32_16x16x32_bf16 v[42:45], v[134:137], v[200:203], v[42:45]
	v_mfma_f32_16x16x32_bf16 v[46:49], v[174:177], v[200:203], v[46:49]
	v_mfma_f32_16x16x32_bf16 v[26:29], v[134:137], v[208:211], v[26:29]
	v_mfma_f32_16x16x32_bf16 v[30:33], v[174:177], v[208:211], v[30:33]
	v_mfma_f32_16x16x32_bf16 v[10:13], v[134:137], v[216:219], v[10:13]
	v_mfma_f32_16x16x32_bf16 v[14:17], v[174:177], v[216:219], v[14:17]
	s_setprio 0
	s_barrier
	s_add_u32 s80, s0, 0x80000
	s_addc_u32 s81, s1, 0
	s_add_i32 s39, s85, s23
	v_lshl_add_u64 v[130:131], s[80:81], 0, v[146:147]
	s_mov_b32 m0, s39
	s_nop 0
	global_load_lds_dwordx4 v[130:131], off
	v_lshl_add_u64 v[130:131], s[80:81], 0, v[150:151]
	s_add_i32 m0, s39, 0x2000
	s_nop 0
	global_load_lds_dwordx4 v[130:131], off
	s_waitcnt vmcnt(6)
	s_barrier
	s_setprio 1
	v_mfma_f32_16x16x32_bf16 v[50:53], v[220:223], v[178:181], v[50:53]
	v_mfma_f32_16x16x32_bf16 v[54:57], v[228:231], v[178:181], v[54:57]
	v_mfma_f32_16x16x32_bf16 v[34:37], v[220:223], v[196:199], v[34:37]
	v_mfma_f32_16x16x32_bf16 v[38:41], v[228:231], v[196:199], v[38:41]
	v_mfma_f32_16x16x32_bf16 v[18:21], v[220:223], v[204:207], v[18:21]
	v_mfma_f32_16x16x32_bf16 v[22:25], v[228:231], v[204:207], v[22:25]
	v_mfma_f32_16x16x32_bf16 v[2:5], v[220:223], v[212:215], v[2:5]
	v_mfma_f32_16x16x32_bf16 v[6:9], v[228:231], v[212:215], v[6:9]
	v_mfma_f32_16x16x32_bf16 v[50:53], v[224:227], v[190:193], v[50:53]
	v_mfma_f32_16x16x32_bf16 v[54:57], v[232:235], v[190:193], v[54:57]
	v_mfma_f32_16x16x32_bf16 v[34:37], v[224:227], v[200:203], v[34:37]
	v_mfma_f32_16x16x32_bf16 v[38:41], v[232:235], v[200:203], v[38:41]
	v_mfma_f32_16x16x32_bf16 v[18:21], v[224:227], v[208:211], v[18:21]
	v_mfma_f32_16x16x32_bf16 v[22:25], v[232:235], v[208:211], v[22:25]
	v_mfma_f32_16x16x32_bf16 v[2:5], v[224:227], v[216:219], v[2:5]
	v_mfma_f32_16x16x32_bf16 v[6:9], v[232:235], v[216:219], v[6:9]
	s_setprio 0
	s_add_i32 s39, 0, 0x18000
	v_add_u32_e32 v142, s39, v161
	s_barrier
	ds_read_b128 v[130:133], v142
	ds_read_b128 v[134:137], v142 offset:1024
	ds_read_b128 v[138:141], v142 offset:2048
	ds_read_b128 v[174:177], v142 offset:3072
	s_add_u32 s2, s2, 0x80000
	s_addc_u32 s3, s3, 0
	s_mov_b32 m0, s33
	v_lshl_add_u64 v[220:221], s[2:3], 0, v[144:145]
	ds_read_b128 v[178:181], v186 offset:32768
	ds_read_b128 v[190:193], v186 offset:33792
	ds_read_b128 v[196:199], v186 offset:34816
	ds_read_b128 v[200:203], v186 offset:35840
	ds_read_b128 v[204:207], v186 offset:36864
	ds_read_b128 v[208:211], v186 offset:37888
	ds_read_b128 v[212:215], v186 offset:38912
	ds_read_b128 v[216:219], v186 offset:39936
	global_load_lds_dwordx4 v[220:221], off
	v_lshl_add_u64 v[220:221], s[2:3], 0, v[148:149]
	s_mov_b32 m0, s40
	s_nop 0
	global_load_lds_dwordx4 v[220:221], off
	s_waitcnt lgkmcnt(8)
	s_barrier
	s_waitcnt lgkmcnt(0)
	s_setprio 1
	s_waitcnt lgkmcnt(0)
	v_mfma_f32_16x16x32_bf16 v[122:125], v[130:133], v[178:181], v[122:125]
	v_mfma_f32_16x16x32_bf16 v[126:129], v[138:141], v[178:181], v[126:129]
	v_mfma_f32_16x16x32_bf16 v[106:109], v[130:133], v[196:199], v[106:109]
	v_mfma_f32_16x16x32_bf16 v[110:113], v[138:141], v[196:199], v[110:113]
	v_mfma_f32_16x16x32_bf16 v[90:93], v[130:133], v[204:207], v[90:93]
	v_mfma_f32_16x16x32_bf16 v[94:97], v[138:141], v[204:207], v[94:97]
	v_mfma_f32_16x16x32_bf16 v[74:77], v[130:133], v[212:215], v[74:77]
	v_mfma_f32_16x16x32_bf16 v[78:81], v[138:141], v[212:215], v[78:81]
	v_mfma_f32_16x16x32_bf16 v[122:125], v[134:137], v[190:193], v[122:125]
	v_mfma_f32_16x16x32_bf16 v[126:129], v[174:177], v[190:193], v[126:129]
	v_mfma_f32_16x16x32_bf16 v[106:109], v[134:137], v[200:203], v[106:109]
	v_mfma_f32_16x16x32_bf16 v[110:113], v[174:177], v[200:203], v[110:113]
	v_mfma_f32_16x16x32_bf16 v[90:93], v[134:137], v[208:211], v[90:93]
	v_mfma_f32_16x16x32_bf16 v[94:97], v[174:177], v[208:211], v[94:97]
	v_mfma_f32_16x16x32_bf16 v[74:77], v[134:137], v[216:219], v[74:77]
	v_mfma_f32_16x16x32_bf16 v[78:81], v[174:177], v[216:219], v[78:81]
	s_setprio 0
	s_barrier
	s_add_i32 s2, 0, 0x1c000
	s_add_i32 s3, s39, s23
	v_add_u32_e32 v142, s2, v161
	v_lshl_add_u64 v[182:183], v[182:183], 0, s[46:47]
	s_mov_b32 m0, s3
	ds_read_b128 v[220:223], v142
	ds_read_b128 v[224:227], v142 offset:1024
	ds_read_b128 v[228:231], v142 offset:2048
	ds_read_b128 v[232:235], v142 offset:3072
	global_load_lds_dwordx4 v[182:183], off
	v_lshl_add_u64 v[182:183], v[236:237], 0, s[46:47]
	s_add_i32 m0, s3, 0x2000
	s_nop 0
	global_load_lds_dwordx4 v[182:183], off
	s_barrier
	s_waitcnt lgkmcnt(0)
	s_setprio 1
	s_waitcnt lgkmcnt(0)
	v_mfma_f32_16x16x32_bf16 v[114:117], v[220:223], v[178:181], v[114:117]
	v_mfma_f32_16x16x32_bf16 v[118:121], v[228:231], v[178:181], v[118:121]
	v_mfma_f32_16x16x32_bf16 v[98:101], v[220:223], v[196:199], v[98:101]
	v_mfma_f32_16x16x32_bf16 v[102:105], v[228:231], v[196:199], v[102:105]
	v_mfma_f32_16x16x32_bf16 v[82:85], v[220:223], v[204:207], v[82:85]
	v_mfma_f32_16x16x32_bf16 v[86:89], v[228:231], v[204:207], v[86:89]
	v_mfma_f32_16x16x32_bf16 v[66:69], v[220:223], v[212:215], v[66:69]
	v_mfma_f32_16x16x32_bf16 v[70:73], v[228:231], v[212:215], v[70:73]
	v_mfma_f32_16x16x32_bf16 v[114:117], v[224:227], v[190:193], v[114:117]
	v_mfma_f32_16x16x32_bf16 v[118:121], v[232:235], v[190:193], v[118:121]
	v_mfma_f32_16x16x32_bf16 v[98:101], v[224:227], v[200:203], v[98:101]
	v_mfma_f32_16x16x32_bf16 v[102:105], v[232:235], v[200:203], v[102:105]
	v_mfma_f32_16x16x32_bf16 v[82:85], v[224:227], v[208:211], v[82:85]
	v_mfma_f32_16x16x32_bf16 v[86:89], v[232:235], v[208:211], v[86:89]
	v_mfma_f32_16x16x32_bf16 v[66:69], v[224:227], v[216:219], v[66:69]
	v_mfma_f32_16x16x32_bf16 v[70:73], v[232:235], v[216:219], v[70:73]
	s_setprio 0
	s_mov_b32 m0, s45
	v_lshl_add_u64 v[182:183], v[238:239], 0, s[46:47]
	s_barrier
	ds_read_b128 v[178:181], v186 offset:49152
	ds_read_b128 v[190:193], v186 offset:50176
	ds_read_b128 v[196:199], v186 offset:51200
	ds_read_b128 v[200:203], v186 offset:52224
	ds_read_b128 v[204:207], v186 offset:53248
	ds_read_b128 v[208:211], v186 offset:54272
	ds_read_b128 v[212:215], v186 offset:55296
	ds_read_b128 v[216:219], v186 offset:56320
	global_load_lds_dwordx4 v[182:183], off
	v_lshl_add_u64 v[182:183], v[240:241], 0, s[46:47]
	s_mov_b32 m0, s48
	s_nop 0
	global_load_lds_dwordx4 v[182:183], off
	s_barrier
	s_waitcnt lgkmcnt(0)
	s_setprio 1
	s_waitcnt lgkmcnt(0)
	v_mfma_f32_16x16x32_bf16 v[58:61], v[130:133], v[178:181], v[58:61]
	v_mfma_f32_16x16x32_bf16 v[62:65], v[138:141], v[178:181], v[62:65]
	v_mfma_f32_16x16x32_bf16 v[42:45], v[130:133], v[196:199], v[42:45]
	v_mfma_f32_16x16x32_bf16 v[46:49], v[138:141], v[196:199], v[46:49]
	v_mfma_f32_16x16x32_bf16 v[26:29], v[130:133], v[204:207], v[26:29]
	v_mfma_f32_16x16x32_bf16 v[30:33], v[138:141], v[204:207], v[30:33]
	v_mfma_f32_16x16x32_bf16 v[10:13], v[130:133], v[212:215], v[10:13]
	v_mfma_f32_16x16x32_bf16 v[14:17], v[138:141], v[212:215], v[14:17]
	v_mfma_f32_16x16x32_bf16 v[58:61], v[134:137], v[190:193], v[58:61]
	v_mfma_f32_16x16x32_bf16 v[62:65], v[174:177], v[190:193], v[62:65]
	v_mfma_f32_16x16x32_bf16 v[42:45], v[134:137], v[200:203], v[42:45]
	v_mfma_f32_16x16x32_bf16 v[46:49], v[174:177], v[200:203], v[46:49]
	v_mfma_f32_16x16x32_bf16 v[26:29], v[134:137], v[208:211], v[26:29]
	v_mfma_f32_16x16x32_bf16 v[30:33], v[174:177], v[208:211], v[30:33]
	v_mfma_f32_16x16x32_bf16 v[10:13], v[134:137], v[216:219], v[10:13]
	v_mfma_f32_16x16x32_bf16 v[14:17], v[174:177], v[216:219], v[14:17]
	s_setprio 0
	s_barrier
	s_add_u32 s0, s0, 0x80080
	s_addc_u32 s1, s1, 0
	s_add_i32 s2, s2, s23
	v_lshl_add_u64 v[130:131], s[0:1], 0, v[146:147]
	s_mov_b32 m0, s2
	s_nop 0
	global_load_lds_dwordx4 v[130:131], off
	v_lshl_add_u64 v[130:131], s[0:1], 0, v[150:151]
	s_add_i32 m0, s2, 0x2000
	s_nop 0
	global_load_lds_dwordx4 v[130:131], off
	s_waitcnt vmcnt(6)
	s_barrier
	s_setprio 1
	v_mfma_f32_16x16x32_bf16 v[50:53], v[220:223], v[178:181], v[50:53]
	v_mfma_f32_16x16x32_bf16 v[54:57], v[228:231], v[178:181], v[54:57]
	v_mfma_f32_16x16x32_bf16 v[34:37], v[220:223], v[196:199], v[34:37]
	v_mfma_f32_16x16x32_bf16 v[38:41], v[228:231], v[196:199], v[38:41]
	v_mfma_f32_16x16x32_bf16 v[18:21], v[220:223], v[204:207], v[18:21]
	v_mfma_f32_16x16x32_bf16 v[22:25], v[228:231], v[204:207], v[22:25]
	v_mfma_f32_16x16x32_bf16 v[2:5], v[220:223], v[212:215], v[2:5]
	v_mfma_f32_16x16x32_bf16 v[6:9], v[228:231], v[212:215], v[6:9]
	v_mfma_f32_16x16x32_bf16 v[50:53], v[224:227], v[190:193], v[50:53]
	v_mfma_f32_16x16x32_bf16 v[54:57], v[232:235], v[190:193], v[54:57]
	v_mfma_f32_16x16x32_bf16 v[34:37], v[224:227], v[200:203], v[34:37]
	v_mfma_f32_16x16x32_bf16 v[38:41], v[232:235], v[200:203], v[38:41]
	v_mfma_f32_16x16x32_bf16 v[18:21], v[224:227], v[208:211], v[18:21]
	v_mfma_f32_16x16x32_bf16 v[22:25], v[232:235], v[208:211], v[22:25]
	v_mfma_f32_16x16x32_bf16 v[2:5], v[224:227], v[216:219], v[2:5]
	v_mfma_f32_16x16x32_bf16 v[6:9], v[232:235], v[216:219], v[6:9]
	s_setprio 0
	s_add_i32 s38, s38, 2
	s_add_u32 s12, s12, 0x100
	s_addc_u32 s13, s13, 0
	s_add_u32 s36, s36, 0x100
	s_addc_u32 s37, s37, 0
	s_cmp_gt_u32 s38, 29
	s_barrier
	s_cbranch_scc0 .LBB0_180
	s_lshl_b32 s2, s8, 8
	s_add_i32 s2, s2, s44
	v_or_b32_e32 v174, s2, v155
	s_cmp_gt_i32 s10, 23
	s_mov_b64 s[0:1], -1
	s_cbranch_scc0 .LBB0_239
	s_cmp_lt_u32 s10, 28
	s_cbranch_scc1 .LBB0_196
	s_lshl_b32 s0, s10, 8
	s_add_i32 s42, s0, 0xffffe400
	v_cmp_gt_i32_e32 vcc, s86, v174
	s_and_saveexec_b64 s[0:1], vcc
	s_cbranch_execz .LBB0_185
	v_mul_f32_e32 v132, 0xbfb8aa3b, v122
	v_ashrrev_i32_e32 v175, 31, v174
	v_exp_f32_e32 v132, v132
	v_lshlrev_b64 v[130:131], 10, v[174:175]
	v_lshl_add_u64 v[130:131], s[26:27], 0, v[130:131]
	v_lshl_add_u64 v[130:131], s[42:43], 1, v[130:131]
	v_lshlrev_b32_e32 v142, 1, v154
	v_lshl_add_u64 v[134:135], v[130:131], 0, v[142:143]
	v_add_f32_e32 v130, 1.0, v132
	v_mul_f32_e32 v131, 0xbfb8aa3b, v126
	v_mul_f32_e32 v132, 0xbfb8aa3b, v123
	v_exp_f32_e32 v131, v131
	v_exp_f32_e32 v132, v132
	v_mul_f32_e32 v133, 0xbfb8aa3b, v127
	v_exp_f32_e32 v133, v133
	v_add_f32_e32 v131, 1.0, v131
	v_add_f32_e32 v132, 1.0, v132
	v_rcp_f32_e32 v131, v131
	v_rcp_f32_e32 v132, v132
	v_mul_f32_e32 v138, 0xbfb8aa3b, v125
	v_mul_f32_e32 v137, 0xbfb8aa3b, v128
	v_mul_f32_e32 v136, v126, v131
	v_mul_f32_e32 v131, v123, v132
	v_add_f32_e32 v132, 1.0, v133
	v_mul_f32_e32 v133, 0xbfb8aa3b, v124
	v_exp_f32_e32 v133, v133
	v_exp_f32_e32 v138, v138
	v_mul_f32_e32 v139, 0xbfb8aa3b, v129
	v_exp_f32_e32 v137, v137
	v_exp_f32_e32 v139, v139
	v_add_f32_e32 v133, 1.0, v133
	v_rcp_f32_e32 v130, v130
	v_rcp_f32_e32 v132, v132
	v_rcp_f32_e32 v133, v133
	v_add_f32_e32 v138, 1.0, v138
	v_add_f32_e32 v137, 1.0, v137
	v_rcp_f32_e32 v138, v138
	v_add_f32_e32 v139, 1.0, v139
	v_rcp_f32_e32 v137, v137
	v_rcp_f32_e32 v139, v139
	v_mul_f32_e32 v130, v122, v130
	v_mul_f32_e32 v132, v127, v132
	v_mul_f32_e32 v133, v124, v133
	v_mul_f32_e32 v138, v125, v138
	v_cvt_pk_bf16_f32 v130, v130, v131
	v_cvt_pk_bf16_f32 v131, v133, v138
	v_mul_f32_e32 v133, 0xbfb8aa3b, v114
	v_cvt_pk_bf16_f32 v132, v136, v132
	v_mul_f32_e32 v137, v128, v137
	v_mul_f32_e32 v139, v129, v139
	v_exp_f32_e32 v138, v133
	v_cvt_pk_bf16_f32 v133, v137, v139
	global_store_dwordx4 v[134:135], v[130:133], off sc0 sc1
	v_mul_f32_e32 v137, 0xbfb8aa3b, v120
	v_mul_f32_e32 v139, 0xbfb8aa3b, v121
	v_mul_f32_e32 v131, 0xbfb8aa3b, v118
	v_mul_f32_e32 v132, 0xbfb8aa3b, v115
	v_exp_f32_e32 v131, v131
	v_exp_f32_e32 v132, v132
	v_mul_f32_e32 v133, 0xbfb8aa3b, v119
	v_exp_f32_e32 v133, v133
	v_add_f32_e32 v131, 1.0, v131
	v_add_f32_e32 v132, 1.0, v132
	v_rcp_f32_e32 v131, v131
	v_rcp_f32_e32 v132, v132
	v_add_f32_e32 v130, 1.0, v138
	v_mul_f32_e32 v138, 0xbfb8aa3b, v117
	v_mul_f32_e32 v136, v118, v131
	v_mul_f32_e32 v131, v115, v132
	v_add_f32_e32 v132, 1.0, v133
	v_mul_f32_e32 v133, 0xbfb8aa3b, v116
	v_exp_f32_e32 v133, v133
	v_exp_f32_e32 v137, v137
	v_exp_f32_e32 v138, v138
	v_exp_f32_e32 v139, v139
	v_add_f32_e32 v133, 1.0, v133
	v_rcp_f32_e32 v130, v130
	v_rcp_f32_e32 v132, v132
	v_rcp_f32_e32 v133, v133
	v_add_f32_e32 v137, 1.0, v137
	v_add_f32_e32 v138, 1.0, v138
	v_add_f32_e32 v139, 1.0, v139
	v_rcp_f32_e32 v137, v137
	v_rcp_f32_e32 v138, v138
	v_rcp_f32_e32 v139, v139
	v_mul_f32_e32 v130, v114, v130
	v_mul_f32_e32 v132, v119, v132
	v_mul_f32_e32 v133, v116, v133
	v_mul_f32_e32 v137, v120, v137
	v_mul_f32_e32 v138, v117, v138
	v_mul_f32_e32 v139, v121, v139
	v_cvt_pk_bf16_f32 v130, v130, v131
	v_cvt_pk_bf16_f32 v131, v133, v138
	v_cvt_pk_bf16_f32 v132, v136, v132
	v_cvt_pk_bf16_f32 v133, v137, v139
	global_store_dwordx4 v[134:135], v[130:133], off offset:256 sc0 sc1
.LBB0_185:
	s_or_b64 exec, exec, s[0:1]
	s_nop 0
	v_or_b32_e32 v130, 16, v174
	v_cmp_gt_i32_e32 vcc, s86, v130
	s_and_saveexec_b64 s[0:1], vcc
	s_cbranch_execz .LBB0_187
	v_mul_f32_e32 v132, 0xbfb8aa3b, v106
	v_ashrrev_i32_e32 v131, 31, v130
	v_exp_f32_e32 v132, v132
	v_lshlrev_b64 v[130:131], 10, v[130:131]
	v_lshl_add_u64 v[130:131], s[26:27], 0, v[130:131]
	v_lshl_add_u64 v[130:131], s[42:43], 1, v[130:131]
	v_lshlrev_b32_e32 v142, 1, v154
	v_lshl_add_u64 v[134:135], v[130:131], 0, v[142:143]
	v_add_f32_e32 v130, 1.0, v132
	v_mul_f32_e32 v131, 0xbfb8aa3b, v110
	v_mul_f32_e32 v132, 0xbfb8aa3b, v107
	v_exp_f32_e32 v131, v131
	v_exp_f32_e32 v132, v132
	v_mul_f32_e32 v133, 0xbfb8aa3b, v111
	v_exp_f32_e32 v133, v133
	v_add_f32_e32 v131, 1.0, v131
	v_add_f32_e32 v132, 1.0, v132
	v_rcp_f32_e32 v131, v131
	v_rcp_f32_e32 v132, v132
	v_mul_f32_e32 v138, 0xbfb8aa3b, v109
	v_mul_f32_e32 v137, 0xbfb8aa3b, v112
	v_mul_f32_e32 v136, v110, v131
	v_mul_f32_e32 v131, v107, v132
	v_add_f32_e32 v132, 1.0, v133
	v_mul_f32_e32 v133, 0xbfb8aa3b, v108
	v_exp_f32_e32 v133, v133
	v_exp_f32_e32 v138, v138
	v_mul_f32_e32 v139, 0xbfb8aa3b, v113
	v_exp_f32_e32 v137, v137
	v_exp_f32_e32 v139, v139
	v_add_f32_e32 v133, 1.0, v133
	v_rcp_f32_e32 v130, v130
	v_rcp_f32_e32 v132, v132
	v_rcp_f32_e32 v133, v133
	v_add_f32_e32 v138, 1.0, v138
	v_add_f32_e32 v137, 1.0, v137
	v_rcp_f32_e32 v138, v138
	v_add_f32_e32 v139, 1.0, v139
	v_rcp_f32_e32 v137, v137
	v_rcp_f32_e32 v139, v139
	v_mul_f32_e32 v130, v106, v130
	v_mul_f32_e32 v132, v111, v132
	v_mul_f32_e32 v133, v108, v133
	v_mul_f32_e32 v138, v109, v138
	v_cvt_pk_bf16_f32 v130, v130, v131
	v_cvt_pk_bf16_f32 v131, v133, v138
	v_mul_f32_e32 v133, 0xbfb8aa3b, v98
	v_cvt_pk_bf16_f32 v132, v136, v132
	v_mul_f32_e32 v137, v112, v137
	v_mul_f32_e32 v139, v113, v139
	v_exp_f32_e32 v138, v133
	v_cvt_pk_bf16_f32 v133, v137, v139
	global_store_dwordx4 v[134:135], v[130:133], off sc0 sc1
	v_mul_f32_e32 v137, 0xbfb8aa3b, v104
	v_mul_f32_e32 v139, 0xbfb8aa3b, v105
	v_mul_f32_e32 v131, 0xbfb8aa3b, v102
	v_mul_f32_e32 v132, 0xbfb8aa3b, v99
	v_exp_f32_e32 v131, v131
	v_exp_f32_e32 v132, v132
	v_mul_f32_e32 v133, 0xbfb8aa3b, v103
	v_exp_f32_e32 v133, v133
	v_add_f32_e32 v131, 1.0, v131
	v_add_f32_e32 v132, 1.0, v132
	v_rcp_f32_e32 v131, v131
	v_rcp_f32_e32 v132, v132
	v_add_f32_e32 v130, 1.0, v138
	v_mul_f32_e32 v138, 0xbfb8aa3b, v101
	v_mul_f32_e32 v136, v102, v131
	v_mul_f32_e32 v131, v99, v132
	v_add_f32_e32 v132, 1.0, v133
	v_mul_f32_e32 v133, 0xbfb8aa3b, v100
	v_exp_f32_e32 v133, v133
	v_exp_f32_e32 v137, v137
	v_exp_f32_e32 v138, v138
	v_exp_f32_e32 v139, v139
	v_add_f32_e32 v133, 1.0, v133
	v_rcp_f32_e32 v130, v130
	v_rcp_f32_e32 v132, v132
	v_rcp_f32_e32 v133, v133
	v_add_f32_e32 v137, 1.0, v137
	v_add_f32_e32 v138, 1.0, v138
	v_add_f32_e32 v139, 1.0, v139
	v_rcp_f32_e32 v137, v137
	v_rcp_f32_e32 v138, v138
	v_rcp_f32_e32 v139, v139
	v_mul_f32_e32 v130, v98, v130
	v_mul_f32_e32 v132, v103, v132
	v_mul_f32_e32 v133, v100, v133
	v_mul_f32_e32 v137, v104, v137
	v_mul_f32_e32 v138, v101, v138
	v_mul_f32_e32 v139, v105, v139
	v_cvt_pk_bf16_f32 v130, v130, v131
	v_cvt_pk_bf16_f32 v131, v133, v138
	v_cvt_pk_bf16_f32 v132, v136, v132
	v_cvt_pk_bf16_f32 v133, v137, v139
	global_store_dwordx4 v[134:135], v[130:133], off offset:256 sc0 sc1
.LBB0_187:
	s_or_b64 exec, exec, s[0:1]
	s_nop 0
	v_or_b32_e32 v130, 32, v174
	v_cmp_gt_i32_e32 vcc, s86, v130
	s_and_saveexec_b64 s[0:1], vcc
	s_cbranch_execz .LBB0_189
	v_mul_f32_e32 v132, 0xbfb8aa3b, v90
	v_ashrrev_i32_e32 v131, 31, v130
	v_exp_f32_e32 v132, v132
	v_lshlrev_b64 v[130:131], 10, v[130:131]
	v_lshl_add_u64 v[130:131], s[26:27], 0, v[130:131]
	v_lshl_add_u64 v[130:131], s[42:43], 1, v[130:131]
	v_lshlrev_b32_e32 v142, 1, v154
	v_lshl_add_u64 v[134:135], v[130:131], 0, v[142:143]
	v_add_f32_e32 v130, 1.0, v132
	v_mul_f32_e32 v131, 0xbfb8aa3b, v94
	v_mul_f32_e32 v132, 0xbfb8aa3b, v91
	v_exp_f32_e32 v131, v131
	v_exp_f32_e32 v132, v132
	v_mul_f32_e32 v133, 0xbfb8aa3b, v95
	v_exp_f32_e32 v133, v133
	v_add_f32_e32 v131, 1.0, v131
	v_add_f32_e32 v132, 1.0, v132
	v_rcp_f32_e32 v131, v131
	v_rcp_f32_e32 v132, v132
	v_mul_f32_e32 v138, 0xbfb8aa3b, v93
	v_mul_f32_e32 v137, 0xbfb8aa3b, v96
	v_mul_f32_e32 v136, v94, v131
	v_mul_f32_e32 v131, v91, v132
	v_add_f32_e32 v132, 1.0, v133
	v_mul_f32_e32 v133, 0xbfb8aa3b, v92
	v_exp_f32_e32 v133, v133
	v_exp_f32_e32 v138, v138
	v_mul_f32_e32 v139, 0xbfb8aa3b, v97
	v_exp_f32_e32 v137, v137
	v_exp_f32_e32 v139, v139
	v_add_f32_e32 v133, 1.0, v133
	v_rcp_f32_e32 v130, v130
	v_rcp_f32_e32 v132, v132
	v_rcp_f32_e32 v133, v133
	v_add_f32_e32 v138, 1.0, v138
	v_add_f32_e32 v137, 1.0, v137
	v_rcp_f32_e32 v138, v138
	v_add_f32_e32 v139, 1.0, v139
	v_rcp_f32_e32 v137, v137
	v_rcp_f32_e32 v139, v139
	v_mul_f32_e32 v130, v90, v130
	v_mul_f32_e32 v132, v95, v132
	v_mul_f32_e32 v133, v92, v133
	v_mul_f32_e32 v138, v93, v138
	v_cvt_pk_bf16_f32 v130, v130, v131
	v_cvt_pk_bf16_f32 v131, v133, v138
	v_mul_f32_e32 v133, 0xbfb8aa3b, v82
	v_cvt_pk_bf16_f32 v132, v136, v132
	v_mul_f32_e32 v137, v96, v137
	v_mul_f32_e32 v139, v97, v139
	v_exp_f32_e32 v138, v133
	v_cvt_pk_bf16_f32 v133, v137, v139
	global_store_dwordx4 v[134:135], v[130:133], off sc0 sc1
	v_mul_f32_e32 v137, 0xbfb8aa3b, v88
	v_mul_f32_e32 v139, 0xbfb8aa3b, v89
	v_mul_f32_e32 v131, 0xbfb8aa3b, v86
	v_mul_f32_e32 v132, 0xbfb8aa3b, v83
	v_exp_f32_e32 v131, v131
	v_exp_f32_e32 v132, v132
	v_mul_f32_e32 v133, 0xbfb8aa3b, v87
	v_exp_f32_e32 v133, v133
	v_add_f32_e32 v131, 1.0, v131
	v_add_f32_e32 v132, 1.0, v132
	v_rcp_f32_e32 v131, v131
	v_rcp_f32_e32 v132, v132
	v_add_f32_e32 v130, 1.0, v138
	v_mul_f32_e32 v138, 0xbfb8aa3b, v85
	v_mul_f32_e32 v136, v86, v131
	v_mul_f32_e32 v131, v83, v132
	v_add_f32_e32 v132, 1.0, v133
	v_mul_f32_e32 v133, 0xbfb8aa3b, v84
	v_exp_f32_e32 v133, v133
	v_exp_f32_e32 v137, v137
	v_exp_f32_e32 v138, v138
	v_exp_f32_e32 v139, v139
	v_add_f32_e32 v133, 1.0, v133
	v_rcp_f32_e32 v130, v130
	v_rcp_f32_e32 v132, v132
	v_rcp_f32_e32 v133, v133
	v_add_f32_e32 v137, 1.0, v137
	v_add_f32_e32 v138, 1.0, v138
	v_add_f32_e32 v139, 1.0, v139
	v_rcp_f32_e32 v137, v137
	v_rcp_f32_e32 v138, v138
	v_rcp_f32_e32 v139, v139
	v_mul_f32_e32 v130, v82, v130
	v_mul_f32_e32 v132, v87, v132
	v_mul_f32_e32 v133, v84, v133
	v_mul_f32_e32 v137, v88, v137
	v_mul_f32_e32 v138, v85, v138
	v_mul_f32_e32 v139, v89, v139
	v_cvt_pk_bf16_f32 v130, v130, v131
	v_cvt_pk_bf16_f32 v131, v133, v138
	v_cvt_pk_bf16_f32 v132, v136, v132
	v_cvt_pk_bf16_f32 v133, v137, v139
	global_store_dwordx4 v[134:135], v[130:133], off offset:256 sc0 sc1
.LBB0_189:
	s_or_b64 exec, exec, s[0:1]
	s_nop 0
	v_or_b32_e32 v130, 48, v174
	v_cmp_gt_i32_e32 vcc, s86, v130
	s_and_saveexec_b64 s[0:1], vcc
	s_cbranch_execz .LBB0_341
	v_mul_f32_e32 v132, 0xbfb8aa3b, v74
	v_ashrrev_i32_e32 v131, 31, v130
	v_exp_f32_e32 v132, v132
	v_lshlrev_b64 v[130:131], 10, v[130:131]
	v_lshl_add_u64 v[130:131], s[26:27], 0, v[130:131]
	v_lshl_add_u64 v[130:131], s[42:43], 1, v[130:131]
	v_lshlrev_b32_e32 v142, 1, v154
	v_lshl_add_u64 v[134:135], v[130:131], 0, v[142:143]
	v_add_f32_e32 v130, 1.0, v132
	v_mul_f32_e32 v131, 0xbfb8aa3b, v78
	v_mul_f32_e32 v132, 0xbfb8aa3b, v75
	v_exp_f32_e32 v131, v131
	v_exp_f32_e32 v132, v132
	v_mul_f32_e32 v133, 0xbfb8aa3b, v79
	v_exp_f32_e32 v133, v133
	v_add_f32_e32 v131, 1.0, v131
	v_add_f32_e32 v132, 1.0, v132
	v_rcp_f32_e32 v131, v131
	v_rcp_f32_e32 v132, v132
	v_mul_f32_e32 v138, 0xbfb8aa3b, v77
	v_mul_f32_e32 v137, 0xbfb8aa3b, v80
	v_mul_f32_e32 v136, v78, v131
	v_mul_f32_e32 v131, v75, v132
	v_add_f32_e32 v132, 1.0, v133
	v_mul_f32_e32 v133, 0xbfb8aa3b, v76
	v_exp_f32_e32 v133, v133
	v_exp_f32_e32 v138, v138
	v_mul_f32_e32 v139, 0xbfb8aa3b, v81
	v_exp_f32_e32 v137, v137
	v_exp_f32_e32 v139, v139
	v_add_f32_e32 v133, 1.0, v133
	v_rcp_f32_e32 v130, v130
	v_rcp_f32_e32 v132, v132
	v_rcp_f32_e32 v133, v133
	v_add_f32_e32 v138, 1.0, v138
	v_add_f32_e32 v137, 1.0, v137
	v_rcp_f32_e32 v138, v138
	v_add_f32_e32 v139, 1.0, v139
	v_rcp_f32_e32 v137, v137
	v_rcp_f32_e32 v139, v139
	v_mul_f32_e32 v130, v74, v130
	v_mul_f32_e32 v132, v79, v132
	v_mul_f32_e32 v133, v76, v133
	v_mul_f32_e32 v138, v77, v138
	v_cvt_pk_bf16_f32 v130, v130, v131
	v_cvt_pk_bf16_f32 v131, v133, v138
	v_mul_f32_e32 v133, 0xbfb8aa3b, v66
	v_cvt_pk_bf16_f32 v132, v136, v132
	v_mul_f32_e32 v137, v80, v137
	v_mul_f32_e32 v139, v81, v139
	v_exp_f32_e32 v138, v133
	v_cvt_pk_bf16_f32 v133, v137, v139
	global_store_dwordx4 v[134:135], v[130:133], off sc0 sc1
	v_mul_f32_e32 v137, 0xbfb8aa3b, v72
	v_mul_f32_e32 v139, 0xbfb8aa3b, v73
	v_mul_f32_e32 v131, 0xbfb8aa3b, v70
	v_mul_f32_e32 v132, 0xbfb8aa3b, v67
	v_exp_f32_e32 v131, v131
	v_exp_f32_e32 v132, v132
	v_mul_f32_e32 v133, 0xbfb8aa3b, v71
	v_exp_f32_e32 v133, v133
	v_add_f32_e32 v131, 1.0, v131
	v_add_f32_e32 v132, 1.0, v132
	v_rcp_f32_e32 v131, v131
	v_rcp_f32_e32 v132, v132
	v_add_f32_e32 v130, 1.0, v138
	v_mul_f32_e32 v138, 0xbfb8aa3b, v69
	v_mul_f32_e32 v136, v70, v131
	v_mul_f32_e32 v131, v67, v132
	v_add_f32_e32 v132, 1.0, v133
	v_mul_f32_e32 v133, 0xbfb8aa3b, v68
	v_exp_f32_e32 v133, v133
	v_exp_f32_e32 v137, v137
	v_exp_f32_e32 v138, v138
	v_exp_f32_e32 v139, v139
	v_add_f32_e32 v133, 1.0, v133
	v_rcp_f32_e32 v130, v130
	v_rcp_f32_e32 v132, v132
	v_rcp_f32_e32 v133, v133
	v_add_f32_e32 v137, 1.0, v137
	v_add_f32_e32 v138, 1.0, v138
	v_add_f32_e32 v139, 1.0, v139
	v_rcp_f32_e32 v137, v137
	v_rcp_f32_e32 v138, v138
	v_rcp_f32_e32 v139, v139
	v_mul_f32_e32 v130, v66, v130
	v_mul_f32_e32 v132, v71, v132
	v_mul_f32_e32 v133, v68, v133
	v_mul_f32_e32 v137, v72, v137
	v_mul_f32_e32 v138, v69, v138
	v_mul_f32_e32 v139, v73, v139
	v_cvt_pk_bf16_f32 v130, v130, v131
	v_cvt_pk_bf16_f32 v131, v133, v138
	v_cvt_pk_bf16_f32 v132, v136, v132
	v_cvt_pk_bf16_f32 v133, v137, v139
	global_store_dwordx4 v[134:135], v[130:133], off offset:256 sc0 sc1
	s_or_b64 exec, exec, s[0:1]
	v_cmp_gt_i32_e32 vcc, s41, v174
	s_and_saveexec_b64 s[0:1], vcc
	s_cbranch_execnz .LBB0_342

.LBB0_192:
	v_mul_f32_e32 v132, 0xbfb8aa3b, v42
	v_ashrrev_i32_e32 v175, 31, v174
	v_exp_f32_e32 v132, v132
	v_lshlrev_b64 v[130:131], 10, v[174:175]
	v_lshl_add_u64 v[130:131], s[26:27], 0, v[130:131]
	v_lshl_add_u64 v[130:131], s[42:43], 1, v[130:131]
	v_lshlrev_b32_e32 v142, 1, v154
	v_lshl_add_u64 v[134:135], v[130:131], 0, v[142:143]
	v_add_f32_e32 v130, 1.0, v132
	v_mul_f32_e32 v131, 0xbfb8aa3b, v46
	v_mul_f32_e32 v132, 0xbfb8aa3b, v43
	v_exp_f32_e32 v131, v131
	v_exp_f32_e32 v132, v132
	v_mul_f32_e32 v133, 0xbfb8aa3b, v47
	v_exp_f32_e32 v133, v133
	v_add_f32_e32 v131, 1.0, v131
	v_add_f32_e32 v132, 1.0, v132
	v_rcp_f32_e32 v131, v131
	v_rcp_f32_e32 v132, v132
	v_mul_f32_e32 v140, 0xbfb8aa3b, v45
	v_mul_f32_e32 v139, 0xbfb8aa3b, v48
	v_mul_f32_e32 v138, v46, v131
	v_mul_f32_e32 v131, v43, v132
	v_add_f32_e32 v132, 1.0, v133
	v_mul_f32_e32 v133, 0xbfb8aa3b, v44
	v_exp_f32_e32 v133, v133
	v_exp_f32_e32 v140, v140
	v_mul_f32_e32 v141, 0xbfb8aa3b, v49
	v_exp_f32_e32 v139, v139
	v_exp_f32_e32 v141, v141
	v_rcp_f32_e32 v130, v130
	v_rcp_f32_e32 v132, v132
	v_add_f32_e32 v133, 1.0, v133
	v_add_f32_e32 v140, 1.0, v140
	v_rcp_f32_e32 v133, v133
	v_add_f32_e32 v139, 1.0, v139
	v_rcp_f32_e32 v140, v140
	v_add_f32_e32 v141, 1.0, v141
	v_rcp_f32_e32 v139, v139
	v_rcp_f32_e32 v141, v141
	s_mov_b32 s3, 0x24000
	v_lshl_add_u64 v[136:137], v[134:135], 0, s[98:99]
	v_mul_f32_e32 v130, v42, v130
	v_mul_f32_e32 v132, v47, v132
	v_add_co_u32_e32 v134, vcc, s3, v134
	v_mul_f32_e32 v133, v44, v133
	v_mul_f32_e32 v140, v45, v140
	v_cvt_pk_bf16_f32 v130, v130, v131
	v_cvt_pk_bf16_f32 v131, v133, v140
	v_cvt_pk_bf16_f32 v132, v138, v132
	v_addc_co_u32_e32 v135, vcc, 0, v135, vcc
	v_mul_f32_e32 v139, v48, v139
	v_mul_f32_e32 v141, v49, v141
	v_cvt_pk_bf16_f32 v133, v139, v141
	global_store_dwordx4 v[134:135], v[130:133], off sc0 sc1
	v_mul_f32_e32 v138, 0xbfb8aa3b, v34
	v_exp_f32_e32 v138, v138
	v_mul_f32_e32 v131, 0xbfb8aa3b, v38
	v_mul_f32_e32 v132, 0xbfb8aa3b, v35
	v_exp_f32_e32 v131, v131
	v_exp_f32_e32 v132, v132
	v_mul_f32_e32 v133, 0xbfb8aa3b, v39
	v_exp_f32_e32 v133, v133
	v_add_f32_e32 v131, 1.0, v131
	v_add_f32_e32 v132, 1.0, v132
	v_rcp_f32_e32 v131, v131
	v_rcp_f32_e32 v132, v132
	v_add_f32_e32 v130, 1.0, v138
	v_mul_f32_e32 v135, 0xbfb8aa3b, v40
	v_mul_f32_e32 v134, v38, v131
	v_mul_f32_e32 v131, v35, v132
	v_add_f32_e32 v132, 1.0, v133
	v_mul_f32_e32 v133, 0xbfb8aa3b, v36
	v_exp_f32_e32 v133, v133
	v_mul_f32_e32 v138, 0xbfb8aa3b, v37
	v_mul_f32_e32 v139, 0xbfb8aa3b, v41
	v_exp_f32_e32 v135, v135
	v_exp_f32_e32 v138, v138
	v_exp_f32_e32 v139, v139
	v_add_f32_e32 v133, 1.0, v133
	v_rcp_f32_e32 v130, v130
	v_rcp_f32_e32 v132, v132
	v_rcp_f32_e32 v133, v133
	v_add_f32_e32 v135, 1.0, v135
	v_add_f32_e32 v138, 1.0, v138
	v_add_f32_e32 v139, 1.0, v139
	v_rcp_f32_e32 v135, v135
	v_rcp_f32_e32 v138, v138
	v_rcp_f32_e32 v139, v139
	v_mul_f32_e32 v130, v34, v130
	v_mul_f32_e32 v132, v39, v132
	v_mul_f32_e32 v133, v36, v133
	v_mul_f32_e32 v135, v40, v135
	v_mul_f32_e32 v138, v37, v138
	v_mul_f32_e32 v139, v41, v139
	v_cvt_pk_bf16_f32 v130, v130, v131
	v_cvt_pk_bf16_f32 v131, v133, v138
	v_cvt_pk_bf16_f32 v132, v134, v132
	v_cvt_pk_bf16_f32 v133, v135, v139
	global_store_dwordx4 v[136:137], v[130:133], off offset:256 sc0 sc1
	s_or_b64 exec, exec, s[0:1]
	v_cmp_gt_i32_e32 vcc, s71, v174
	s_and_saveexec_b64 s[0:1], vcc
	s_cbranch_execnz .LBB0_344

.LBB0_194:
	v_mul_f32_e32 v132, 0xbfb8aa3b, v10
	v_ashrrev_i32_e32 v175, 31, v174
	v_exp_f32_e32 v132, v132
	v_lshlrev_b64 v[130:131], 10, v[174:175]
	v_lshl_add_u64 v[130:131], s[26:27], 0, v[130:131]
	v_lshl_add_u64 v[130:131], s[42:43], 1, v[130:131]
	v_lshlrev_b32_e32 v142, 1, v154
	v_lshl_add_u64 v[134:135], v[130:131], 0, v[142:143]
	v_add_f32_e32 v130, 1.0, v132
	v_mul_f32_e32 v131, 0xbfb8aa3b, v14
	v_mul_f32_e32 v132, 0xbfb8aa3b, v11
	v_exp_f32_e32 v131, v131
	v_exp_f32_e32 v132, v132
	v_mul_f32_e32 v133, 0xbfb8aa3b, v15
	v_exp_f32_e32 v133, v133
	v_add_f32_e32 v131, 1.0, v131
	v_add_f32_e32 v132, 1.0, v132
	v_rcp_f32_e32 v131, v131
	v_rcp_f32_e32 v132, v132
	v_mul_f32_e32 v140, 0xbfb8aa3b, v13
	v_mul_f32_e32 v139, 0xbfb8aa3b, v16
	v_mul_f32_e32 v138, v14, v131
	v_mul_f32_e32 v131, v11, v132
	v_add_f32_e32 v132, 1.0, v133
	v_mul_f32_e32 v133, 0xbfb8aa3b, v12
	v_exp_f32_e32 v133, v133
	v_exp_f32_e32 v140, v140
	v_mul_f32_e32 v141, 0xbfb8aa3b, v17
	v_exp_f32_e32 v139, v139
	v_exp_f32_e32 v141, v141
	v_rcp_f32_e32 v130, v130
	v_rcp_f32_e32 v132, v132
	v_add_f32_e32 v133, 1.0, v133
	v_add_f32_e32 v140, 1.0, v140
	v_rcp_f32_e32 v133, v133
	v_add_f32_e32 v139, 1.0, v139
	v_rcp_f32_e32 v140, v140
	v_add_f32_e32 v141, 1.0, v141
	v_rcp_f32_e32 v139, v139
	v_rcp_f32_e32 v141, v141
	s_mov_b32 s3, 0x2c000
	v_lshl_add_u64 v[136:137], v[134:135], 0, s[88:89]
	v_mul_f32_e32 v130, v10, v130
	v_mul_f32_e32 v132, v15, v132
	v_add_co_u32_e32 v134, vcc, s3, v134
	v_mul_f32_e32 v133, v12, v133
	v_mul_f32_e32 v140, v13, v140
	v_cvt_pk_bf16_f32 v130, v130, v131
	v_cvt_pk_bf16_f32 v131, v133, v140
	v_cvt_pk_bf16_f32 v132, v138, v132
	v_addc_co_u32_e32 v135, vcc, 0, v135, vcc
	v_mul_f32_e32 v139, v16, v139
	v_mul_f32_e32 v141, v17, v141
	v_cvt_pk_bf16_f32 v133, v139, v141
	global_store_dwordx4 v[134:135], v[130:133], off sc0 sc1
	v_mul_f32_e32 v138, 0xbfb8aa3b, v2
	v_exp_f32_e32 v138, v138
	v_mul_f32_e32 v131, 0xbfb8aa3b, v6
	v_mul_f32_e32 v132, 0xbfb8aa3b, v3
	v_exp_f32_e32 v131, v131
	v_exp_f32_e32 v132, v132
	v_mul_f32_e32 v133, 0xbfb8aa3b, v7
	v_exp_f32_e32 v133, v133
	v_add_f32_e32 v131, 1.0, v131
	v_add_f32_e32 v132, 1.0, v132
	v_rcp_f32_e32 v131, v131
	v_rcp_f32_e32 v132, v132
	v_add_f32_e32 v130, 1.0, v138
	v_mul_f32_e32 v135, 0xbfb8aa3b, v8
	v_mul_f32_e32 v134, v6, v131
	v_mul_f32_e32 v131, v3, v132
	v_add_f32_e32 v132, 1.0, v133
	v_mul_f32_e32 v133, 0xbfb8aa3b, v4
	v_exp_f32_e32 v133, v133
	v_mul_f32_e32 v138, 0xbfb8aa3b, v5
	v_mul_f32_e32 v139, 0xbfb8aa3b, v9
	v_exp_f32_e32 v135, v135
	v_exp_f32_e32 v138, v138
	v_exp_f32_e32 v139, v139
	v_add_f32_e32 v133, 1.0, v133
	v_rcp_f32_e32 v130, v130
	v_rcp_f32_e32 v132, v132
	v_rcp_f32_e32 v133, v133
	v_add_f32_e32 v135, 1.0, v135
	v_add_f32_e32 v138, 1.0, v138
	v_add_f32_e32 v139, 1.0, v139
	v_rcp_f32_e32 v135, v135
	v_rcp_f32_e32 v138, v138
	v_rcp_f32_e32 v139, v139
	v_mul_f32_e32 v130, v2, v130
	v_mul_f32_e32 v132, v7, v132
	v_mul_f32_e32 v133, v4, v133
	v_mul_f32_e32 v135, v8, v135
	v_mul_f32_e32 v138, v5, v138
	v_mul_f32_e32 v139, v9, v139
	v_cvt_pk_bf16_f32 v130, v130, v131
	v_cvt_pk_bf16_f32 v131, v133, v138
	v_cvt_pk_bf16_f32 v132, v134, v132
	v_cvt_pk_bf16_f32 v133, v135, v139
	global_store_dwordx4 v[136:137], v[130:133], off offset:256 sc0 sc1

.LBB0_196:
	s_and_b64 vcc, exec, s[0:1]
	s_cbranch_vccz .LBB0_238
	s_ashr_i32 s11, s2, 11
	s_mul_i32 s1, s11, 0x81e
	s_mul_hi_i32 s0, s11, 0x81e
	s_add_u32 s8, s1, 30
	v_lshl_add_u32 v142, s10, 7, v184
	s_addc_u32 s9, s0, 0
	v_cmp_gt_i32_e32 vcc, s86, v174
	s_and_saveexec_b64 s[0:1], vcc
	s_cbranch_execz .LBB0_202
	v_mul_f32_e32 v131, 0xbfb8aa3b, v118
	v_mul_f32_e32 v133, 0xbfb8aa3b, v119
	v_exp_f32_e32 v131, v131
	v_exp_f32_e32 v133, v133
	v_mul_f32_e32 v130, 0xbfb8aa3b, v114
	v_mul_f32_e32 v137, 0xbfb8aa3b, v121
	v_add_f32_e32 v131, 1.0, v131
	v_add_f32_e32 v133, 1.0, v133
	v_rcp_f32_e32 v132, v131
	v_rcp_f32_e32 v133, v133
	v_mul_f32_e32 v131, 0xbfb8aa3b, v115
	v_exp_f32_e32 v130, v130
	v_exp_f32_e32 v131, v131
	v_pk_mul_f32 v[134:135], v[126:127], v[132:133]
	v_mul_f32_e32 v133, 0xbfb8aa3b, v120
	v_exp_f32_e32 v133, v133
	v_mul_f32_e32 v132, 0xbfb8aa3b, v116
	v_exp_f32_e32 v132, v132
	v_exp_f32_e32 v137, v137
	v_add_f32_e32 v133, 1.0, v133
	v_rcp_f32_e32 v136, v133
	v_mul_f32_e32 v133, 0xbfb8aa3b, v117
	v_exp_f32_e32 v133, v133
	v_add_f32_e32 v130, 1.0, v130
	v_add_f32_e32 v131, 1.0, v131
	v_add_f32_e32 v132, 1.0, v132
	v_add_f32_e32 v133, 1.0, v133
	v_add_f32_e32 v137, 1.0, v137
	v_rcp_f32_e32 v130, v130
	v_rcp_f32_e32 v131, v131
	v_rcp_f32_e32 v132, v132
	v_rcp_f32_e32 v133, v133
	v_rcp_f32_e32 v137, v137
	v_pk_mul_f32 v[130:131], v[122:123], v[130:131]
	v_cmp_lt_i32_e32 vcc, s49, v174
	v_pk_mul_f32 v[132:133], v[124:125], v[132:133]
	v_pk_mul_f32 v[136:137], v[128:129], v[136:137]
	v_cvt_pk_bf16_f32 v138, v130, v131
	v_cvt_pk_bf16_f32 v139, v132, v133
	v_cvt_pk_bf16_f32 v140, v134, v135
	s_nop 0
	v_cvt_pk_bf16_f32 v141, v136, v137
	s_and_saveexec_b64 s[2:3], vcc
	s_xor_b64 s[2:3], exec, s[2:3]
	s_cbranch_execz .LBB0_200
	v_add_u32_e32 v175, 0xffffe000, v174
	v_lshrrev_b32_e32 v175, 2, v175
	v_mad_u64_u32 v[176:177], s[12:13], v175, 34, v[156:157]
	v_lshlrev_b64 v[176:177], 10, v[176:177]
	v_lshl_add_u64 v[176:177], s[34:35], 0, v[176:177]
	v_lshl_add_u64 v[176:177], v[142:143], 1, v[176:177]
	global_store_dwordx4 v[176:177], v[138:141], off sc0 sc1
	s_nop 1
	v_mad_u64_u32 v[138:139], s[12:13], v175, 30, v[158:159]
	v_lshlrev_b64 v[138:139], 11, v[138:139]
	v_lshl_add_u64 v[138:139], s[94:95], 0, v[138:139]
	v_lshl_add_u64 v[138:139], v[142:143], 2, v[138:139]
	global_store_dwordx4 v[138:139], v[130:133], off sc0 sc1
	global_store_dwordx4 v[138:139], v[134:137], off offset:16 sc0 sc1
.LBB0_200:
	s_andn2_saveexec_b64 s[2:3], s[2:3]
	s_cbranch_execz .LBB0_202
	v_and_b32_e32 v130, 0x7cf, v174
	v_mov_b32_e32 v131, v143
	v_lshl_add_u64 v[130:131], s[8:9], 0, v[130:131]
	v_lshlrev_b64 v[130:131], 10, v[130:131]
	v_lshl_add_u64 v[130:131], s[28:29], 0, v[130:131]
	v_lshl_add_u64 v[130:131], v[142:143], 1, v[130:131]
	global_store_dwordx4 v[130:131], v[138:141], off sc0 sc1
.LBB0_202:
	s_or_b64 exec, exec, s[0:1]
	v_or_b32_e32 v175, 16, v174
	v_cmp_gt_i32_e32 vcc, s86, v175
	s_and_saveexec_b64 s[0:1], vcc
	s_cbranch_execz .LBB0_207
	v_mul_f32_e32 v131, 0xbfb8aa3b, v102
	v_mul_f32_e32 v133, 0xbfb8aa3b, v103
	v_exp_f32_e32 v131, v131
	v_exp_f32_e32 v133, v133
	v_mul_f32_e32 v130, 0xbfb8aa3b, v98
	v_mul_f32_e32 v137, 0xbfb8aa3b, v105
	v_add_f32_e32 v131, 1.0, v131
	v_add_f32_e32 v133, 1.0, v133
	v_rcp_f32_e32 v132, v131
	v_rcp_f32_e32 v133, v133
	v_mul_f32_e32 v131, 0xbfb8aa3b, v99
	v_exp_f32_e32 v130, v130
	v_exp_f32_e32 v131, v131
	v_pk_mul_f32 v[134:135], v[110:111], v[132:133]
	v_mul_f32_e32 v133, 0xbfb8aa3b, v104
	v_exp_f32_e32 v133, v133
	v_mul_f32_e32 v132, 0xbfb8aa3b, v100
	v_exp_f32_e32 v132, v132
	v_exp_f32_e32 v137, v137
	v_add_f32_e32 v133, 1.0, v133
	v_rcp_f32_e32 v136, v133
	v_mul_f32_e32 v133, 0xbfb8aa3b, v101
	v_exp_f32_e32 v133, v133
	v_add_f32_e32 v130, 1.0, v130
	v_add_f32_e32 v131, 1.0, v131
	v_add_f32_e32 v132, 1.0, v132
	v_add_f32_e32 v133, 1.0, v133
	v_add_f32_e32 v137, 1.0, v137
	v_rcp_f32_e32 v130, v130
	v_rcp_f32_e32 v131, v131
	v_rcp_f32_e32 v132, v132
	v_rcp_f32_e32 v133, v133
	v_rcp_f32_e32 v137, v137
	v_pk_mul_f32 v[130:131], v[106:107], v[130:131]
	v_cmp_lt_i32_e32 vcc, s49, v175
	v_pk_mul_f32 v[132:133], v[108:109], v[132:133]
	v_pk_mul_f32 v[136:137], v[112:113], v[136:137]
	v_cvt_pk_bf16_f32 v138, v130, v131
	v_cvt_pk_bf16_f32 v139, v132, v133
	v_cvt_pk_bf16_f32 v140, v134, v135
	s_nop 0
	v_cvt_pk_bf16_f32 v141, v136, v137
	s_and_saveexec_b64 s[2:3], vcc
	s_xor_b64 s[2:3], exec, s[2:3]
	s_cbranch_execz .LBB0_205
	v_add_u32_e32 v175, 0xffffe010, v174
	v_lshrrev_b32_e32 v175, 2, v175
	v_mad_u64_u32 v[176:177], s[12:13], v175, 34, v[156:157]
	v_lshlrev_b64 v[176:177], 10, v[176:177]
	v_lshl_add_u64 v[176:177], s[34:35], 0, v[176:177]
	v_lshl_add_u64 v[176:177], v[142:143], 1, v[176:177]
	global_store_dwordx4 v[176:177], v[138:141], off sc0 sc1
	s_nop 1
	v_mad_u64_u32 v[138:139], s[12:13], v175, 30, v[158:159]
	v_lshlrev_b64 v[138:139], 11, v[138:139]
	v_lshl_add_u64 v[138:139], s[94:95], 0, v[138:139]
	v_lshl_add_u64 v[138:139], v[142:143], 2, v[138:139]
	global_store_dwordx4 v[138:139], v[130:133], off sc0 sc1
	global_store_dwordx4 v[138:139], v[134:137], off offset:16 sc0 sc1
.LBB0_205:
	s_andn2_saveexec_b64 s[2:3], s[2:3]
	s_cbranch_execz .LBB0_207
	v_and_b32_e32 v130, 0x7df, v175
	v_mov_b32_e32 v131, v143
	v_lshl_add_u64 v[130:131], s[8:9], 0, v[130:131]
	v_lshlrev_b64 v[130:131], 10, v[130:131]
	v_lshl_add_u64 v[130:131], s[28:29], 0, v[130:131]
	v_lshl_add_u64 v[130:131], v[142:143], 1, v[130:131]
	global_store_dwordx4 v[130:131], v[138:141], off sc0 sc1
.LBB0_207:
	s_or_b64 exec, exec, s[0:1]
	v_or_b32_e32 v175, 32, v174
	s_mul_hi_i32 s1, s11, 30
	s_mul_i32 s0, s11, 30
	v_cmp_gt_i32_e32 vcc, s86, v175
	s_and_saveexec_b64 s[2:3], vcc
	s_cbranch_execz .LBB0_212
	v_mul_f32_e32 v131, 0xbfb8aa3b, v86
	v_mul_f32_e32 v132, 0xbfb8aa3b, v83
	v_exp_f32_e32 v131, v131
	v_exp_f32_e32 v133, v132
	v_mul_f32_e32 v132, 0xbfb8aa3b, v87
	v_exp_f32_e32 v134, v132
	v_add_f32_e32 v131, 1.0, v131
	v_rcp_f32_e32 v132, v131
	v_add_f32_e32 v131, 1.0, v133
	v_add_f32_e32 v133, 1.0, v134
	v_mul_f32_e32 v134, 0xbfb8aa3b, v84
	v_exp_f32_e32 v134, v134
	v_mul_f32_e32 v135, 0xbfb8aa3b, v88
	v_exp_f32_e32 v135, v135
	v_mul_f32_e32 v130, 0xbfb8aa3b, v82
	v_add_f32_e32 v134, 1.0, v134
	v_rcp_f32_e32 v136, v134
	v_add_f32_e32 v134, 1.0, v135
	v_mul_f32_e32 v135, 0xbfb8aa3b, v85
	v_exp_f32_e32 v135, v135
	v_mul_f32_e32 v137, 0xbfb8aa3b, v89
	v_exp_f32_e32 v130, v130
	v_exp_f32_e32 v139, v137
	v_rcp_f32_e32 v138, v134
	v_add_f32_e32 v134, 1.0, v135
	v_add_f32_e32 v130, 1.0, v130
	v_rcp_f32_e32 v137, v134
	v_add_f32_e32 v134, 1.0, v139
	v_rcp_f32_e32 v130, v130
	v_rcp_f32_e32 v131, v131
	v_rcp_f32_e32 v133, v133
	v_rcp_f32_e32 v139, v134
	v_pk_mul_f32 v[136:137], v[92:93], v[136:137]
	v_pk_mul_f32 v[134:135], v[90:91], v[130:131]
	v_pk_mul_f32 v[130:131], v[94:95], v[132:133]
	v_pk_mul_f32 v[132:133], v[96:97], v[138:139]
	v_cmp_lt_i32_e32 vcc, s49, v175
	s_mov_b64 s[12:13], 0
	v_cvt_pk_bf16_f32 v138, v134, v135
	v_cvt_pk_bf16_f32 v139, v136, v137
	v_cvt_pk_bf16_f32 v140, v130, v131
	v_cvt_pk_bf16_f32 v141, v132, v133
	s_and_saveexec_b64 s[14:15], vcc
	s_xor_b64 s[14:15], exec, s[14:15]
	s_cbranch_execz .LBB0_345
	v_add_u32_e32 v175, 0xffffe020, v174
	v_lshrrev_b32_e32 v175, 2, v175
	v_mad_u64_u32 v[176:177], s[12:13], v175, 34, v[156:157]
	v_lshlrev_b64 v[176:177], 10, v[176:177]
	v_lshl_add_u64 v[176:177], s[34:35], 0, v[176:177]
	v_lshl_add_u64 v[176:177], v[142:143], 1, v[176:177]
	global_store_dwordx4 v[176:177], v[138:141], off sc0 sc1
	v_mad_u64_u32 v[176:177], s[12:13], v175, 30, v[158:159]
	s_mov_b64 s[12:13], exec
	s_or_saveexec_b64 s[14:15], s[14:15]
	v_mov_b64_e32 v[178:179], 0xa13c000
	s_xor_b64 exec, exec, s[14:15]
	s_cbranch_execnz .LBB0_346

.LBB0_211:
	v_readlane_b32 s12, v248, 38
	v_readlane_b32 s13, v248, 39
	s_load_dwordx16 s[52:67], s[12:13], 0x40
	v_lshlrev_b64 v[140:141], 11, v[176:177]
	s_waitcnt lgkmcnt(0)
	v_readlane_b32 s52, v248, 38
	v_readlane_b32 s53, v248, 39
	v_lshl_add_u64 v[138:139], s[66:67], 0, v[178:179]
	v_lshl_add_u64 v[138:139], v[138:139], 0, v[140:141]
	v_lshl_add_u64 v[138:139], v[142:143], 2, v[138:139]
	global_store_dwordx4 v[138:139], v[134:137], off sc0 sc1
	global_store_dwordx4 v[138:139], v[130:133], off offset:16 sc0 sc1
.LBB0_212:
	s_or_b64 exec, exec, s[2:3]
	v_or_b32_e32 v175, 48, v174
	v_cmp_gt_i32_e32 vcc, s86, v175
	s_and_saveexec_b64 s[2:3], vcc
	s_cbranch_execz .LBB0_217
	v_mul_f32_e32 v131, 0xbfb8aa3b, v70
	v_mul_f32_e32 v132, 0xbfb8aa3b, v67
	v_exp_f32_e32 v131, v131
	v_exp_f32_e32 v133, v132
	v_mul_f32_e32 v132, 0xbfb8aa3b, v71
	v_exp_f32_e32 v134, v132
	v_add_f32_e32 v131, 1.0, v131
	v_rcp_f32_e32 v132, v131
	v_add_f32_e32 v131, 1.0, v133
	v_add_f32_e32 v133, 1.0, v134
	v_mul_f32_e32 v134, 0xbfb8aa3b, v68
	v_exp_f32_e32 v134, v134
	v_mul_f32_e32 v135, 0xbfb8aa3b, v72
	v_exp_f32_e32 v135, v135
	v_mul_f32_e32 v130, 0xbfb8aa3b, v66
	v_add_f32_e32 v134, 1.0, v134
	v_rcp_f32_e32 v136, v134
	v_add_f32_e32 v134, 1.0, v135
	v_mul_f32_e32 v135, 0xbfb8aa3b, v69
	v_exp_f32_e32 v135, v135
	v_mul_f32_e32 v137, 0xbfb8aa3b, v73
	v_exp_f32_e32 v130, v130
	v_exp_f32_e32 v139, v137
	v_rcp_f32_e32 v138, v134
	v_add_f32_e32 v134, 1.0, v135
	v_add_f32_e32 v130, 1.0, v130
	v_rcp_f32_e32 v137, v134
	v_add_f32_e32 v134, 1.0, v139
	v_rcp_f32_e32 v130, v130
	v_rcp_f32_e32 v131, v131
	v_rcp_f32_e32 v133, v133
	v_rcp_f32_e32 v139, v134
	v_pk_mul_f32 v[136:137], v[76:77], v[136:137]
	v_pk_mul_f32 v[134:135], v[74:75], v[130:131]
	v_pk_mul_f32 v[130:131], v[78:79], v[132:133]
	v_pk_mul_f32 v[132:133], v[80:81], v[138:139]
	v_cmp_lt_i32_e32 vcc, s49, v175
	s_mov_b64 s[12:13], 0
	v_cvt_pk_bf16_f32 v138, v134, v135
	v_cvt_pk_bf16_f32 v139, v136, v137
	v_cvt_pk_bf16_f32 v140, v130, v131
	v_cvt_pk_bf16_f32 v141, v132, v133
	s_and_saveexec_b64 s[14:15], vcc
	s_xor_b64 s[14:15], exec, s[14:15]
	s_cbranch_execz .LBB0_349
	v_add_u32_e32 v175, 0xffffe030, v174
	v_lshrrev_b32_e32 v175, 2, v175
	v_mad_u64_u32 v[176:177], s[12:13], v175, 34, v[156:157]
	v_lshlrev_b64 v[176:177], 10, v[176:177]
	v_lshl_add_u64 v[176:177], s[34:35], 0, v[176:177]
	v_lshl_add_u64 v[176:177], v[142:143], 1, v[176:177]
	global_store_dwordx4 v[176:177], v[138:141], off sc0 sc1
	v_mad_u64_u32 v[176:177], s[12:13], v175, 30, v[158:159]
	s_mov_b64 s[12:13], exec
	s_or_saveexec_b64 s[14:15], s[14:15]
	v_mov_b64_e32 v[178:179], 0xa13c000
	s_xor_b64 exec, exec, s[14:15]
	s_cbranch_execnz .LBB0_350

.LBB0_216:
	v_readlane_b32 s0, v248, 38
	v_readlane_b32 s1, v248, 39
	s_load_dwordx16 s[52:67], s[0:1], 0x40
	v_lshlrev_b64 v[140:141], 11, v[176:177]
	s_waitcnt lgkmcnt(0)
	v_readlane_b32 s52, v248, 38
	v_readlane_b32 s53, v248, 39
	v_lshl_add_u64 v[138:139], s[66:67], 0, v[178:179]
	v_lshl_add_u64 v[138:139], v[138:139], 0, v[140:141]
	v_lshl_add_u64 v[138:139], v[142:143], 2, v[138:139]
	global_store_dwordx4 v[138:139], v[134:137], off sc0 sc1
	global_store_dwordx4 v[138:139], v[130:133], off offset:16 sc0 sc1
.LBB0_217:
	s_or_b64 exec, exec, s[2:3]
	v_add_u32_e32 v178, 0x80, v174
	v_ashrrev_i32_e32 v175, 11, v178
	v_mul_hi_i32_i24_e32 v131, 0x81e, v175
	v_mul_i32_i24_e32 v130, 0x81e, v175
	v_lshl_add_u64 v[176:177], v[130:131], 0, 30
	v_cmp_gt_i32_e32 vcc, s41, v174
	s_and_saveexec_b64 s[0:1], vcc
	s_cbranch_execz .LBB0_222
	v_mul_f32_e32 v131, 0xbfb8aa3b, v54
	v_mul_f32_e32 v133, 0xbfb8aa3b, v55
	v_exp_f32_e32 v131, v131
	v_exp_f32_e32 v133, v133
	v_mul_f32_e32 v130, 0xbfb8aa3b, v50
	v_mul_f32_e32 v137, 0xbfb8aa3b, v57
	v_add_f32_e32 v131, 1.0, v131
	v_add_f32_e32 v133, 1.0, v133
	v_rcp_f32_e32 v132, v131
	v_rcp_f32_e32 v133, v133
	v_mul_f32_e32 v131, 0xbfb8aa3b, v51
	v_exp_f32_e32 v130, v130
	v_exp_f32_e32 v131, v131
	v_pk_mul_f32 v[134:135], v[62:63], v[132:133]
	v_mul_f32_e32 v133, 0xbfb8aa3b, v56
	v_exp_f32_e32 v133, v133
	v_mul_f32_e32 v132, 0xbfb8aa3b, v52
	v_exp_f32_e32 v132, v132
	v_exp_f32_e32 v137, v137
	v_add_f32_e32 v133, 1.0, v133
	v_rcp_f32_e32 v136, v133
	v_mul_f32_e32 v133, 0xbfb8aa3b, v53
	v_exp_f32_e32 v133, v133
	v_add_f32_e32 v130, 1.0, v130
	v_add_f32_e32 v131, 1.0, v131
	v_add_f32_e32 v132, 1.0, v132
	v_add_f32_e32 v133, 1.0, v133
	v_add_f32_e32 v137, 1.0, v137
	v_rcp_f32_e32 v130, v130
	v_rcp_f32_e32 v131, v131
	v_rcp_f32_e32 v132, v132
	v_rcp_f32_e32 v133, v133
	v_rcp_f32_e32 v137, v137
	s_movk_i32 s2, 0x1f7f
	v_pk_mul_f32 v[130:131], v[58:59], v[130:131]
	v_pk_mul_f32 v[132:133], v[60:61], v[132:133]
	v_pk_mul_f32 v[136:137], v[64:65], v[136:137]
	v_cmp_lt_i32_e32 vcc, s2, v174
	v_cvt_pk_bf16_f32 v138, v130, v131
	v_cvt_pk_bf16_f32 v139, v132, v133
	v_cvt_pk_bf16_f32 v140, v134, v135
	v_cvt_pk_bf16_f32 v141, v136, v137
	s_and_saveexec_b64 s[2:3], vcc
	s_xor_b64 s[2:3], exec, s[2:3]
	s_cbranch_execz .LBB0_220
	v_add_u32_e32 v178, 0xffffe080, v174
	v_lshrrev_b32_e32 v180, 2, v178
	v_mad_u64_u32 v[178:179], s[8:9], v180, 34, v[156:157]
	v_lshlrev_b64 v[178:179], 10, v[178:179]
	v_lshl_add_u64 v[178:179], s[34:35], 0, v[178:179]
	v_lshl_add_u64 v[178:179], v[142:143], 1, v[178:179]
	global_store_dwordx4 v[178:179], v[138:141], off sc0 sc1
	s_nop 1
	v_mad_u64_u32 v[138:139], s[8:9], v180, 30, v[158:159]
	v_lshlrev_b64 v[138:139], 11, v[138:139]
	v_lshl_add_u64 v[138:139], s[94:95], 0, v[138:139]
	v_lshl_add_u64 v[138:139], v[142:143], 2, v[138:139]
	global_store_dwordx4 v[138:139], v[130:133], off sc0 sc1
	global_store_dwordx4 v[138:139], v[134:137], off offset:16 sc0 sc1
.LBB0_220:
	s_andn2_saveexec_b64 s[2:3], s[2:3]
	s_cbranch_execz .LBB0_222
	v_and_b32_e32 v130, 0x7cf, v178
	v_mov_b32_e32 v131, v143
	v_lshl_add_u64 v[130:131], v[176:177], 0, v[130:131]
	v_lshlrev_b64 v[130:131], 10, v[130:131]
	v_lshl_add_u64 v[130:131], s[28:29], 0, v[130:131]
	v_lshl_add_u64 v[130:131], v[142:143], 1, v[130:131]
	global_store_dwordx4 v[130:131], v[138:141], off sc0 sc1
.LBB0_222:
	s_or_b64 exec, exec, s[0:1]
	v_cmp_gt_i32_e32 vcc, s87, v174
	s_and_saveexec_b64 s[0:1], vcc
	s_cbranch_execz .LBB0_227
	v_mul_f32_e32 v131, 0xbfb8aa3b, v38
	v_mul_f32_e32 v133, 0xbfb8aa3b, v39
	v_exp_f32_e32 v131, v131
	v_exp_f32_e32 v133, v133
	v_mul_f32_e32 v130, 0xbfb8aa3b, v34
	v_mul_f32_e32 v137, 0xbfb8aa3b, v41
	v_add_f32_e32 v131, 1.0, v131
	v_add_f32_e32 v133, 1.0, v133
	v_rcp_f32_e32 v132, v131
	v_rcp_f32_e32 v133, v133
	v_mul_f32_e32 v131, 0xbfb8aa3b, v35
	v_exp_f32_e32 v130, v130
	v_exp_f32_e32 v131, v131
	v_pk_mul_f32 v[134:135], v[46:47], v[132:133]
	v_mul_f32_e32 v133, 0xbfb8aa3b, v40
	v_exp_f32_e32 v133, v133
	v_mul_f32_e32 v132, 0xbfb8aa3b, v36
	v_exp_f32_e32 v132, v132
	v_exp_f32_e32 v137, v137
	v_add_f32_e32 v133, 1.0, v133
	v_rcp_f32_e32 v136, v133
	v_mul_f32_e32 v133, 0xbfb8aa3b, v37
	v_exp_f32_e32 v133, v133
	v_add_f32_e32 v130, 1.0, v130
	v_add_f32_e32 v131, 1.0, v131
	v_add_f32_e32 v132, 1.0, v132
	v_add_f32_e32 v133, 1.0, v133
	v_add_f32_e32 v137, 1.0, v137
	v_rcp_f32_e32 v130, v130
	v_rcp_f32_e32 v131, v131
	v_rcp_f32_e32 v132, v132
	v_rcp_f32_e32 v133, v133
	v_rcp_f32_e32 v137, v137
	s_movk_i32 s2, 0x1f6f
	v_pk_mul_f32 v[130:131], v[42:43], v[130:131]
	v_pk_mul_f32 v[132:133], v[44:45], v[132:133]
	v_pk_mul_f32 v[136:137], v[48:49], v[136:137]
	v_cmp_lt_i32_e32 vcc, s2, v174
	v_cvt_pk_bf16_f32 v138, v130, v131
	v_cvt_pk_bf16_f32 v139, v132, v133
	v_cvt_pk_bf16_f32 v140, v134, v135
	v_cvt_pk_bf16_f32 v141, v136, v137
	s_and_saveexec_b64 s[2:3], vcc
	s_xor_b64 s[2:3], exec, s[2:3]
	s_cbranch_execz .LBB0_225
	v_add_u32_e32 v178, 0xffffe090, v174
	v_lshrrev_b32_e32 v180, 2, v178
	v_mad_u64_u32 v[178:179], s[8:9], v180, 34, v[156:157]
	v_lshlrev_b64 v[178:179], 10, v[178:179]
	v_lshl_add_u64 v[178:179], s[34:35], 0, v[178:179]
	v_lshl_add_u64 v[178:179], v[142:143], 1, v[178:179]
	global_store_dwordx4 v[178:179], v[138:141], off sc0 sc1
	s_nop 1
	v_mad_u64_u32 v[138:139], s[8:9], v180, 30, v[158:159]
	v_lshlrev_b64 v[138:139], 11, v[138:139]
	v_lshl_add_u64 v[138:139], s[94:95], 0, v[138:139]
	v_lshl_add_u64 v[138:139], v[142:143], 2, v[138:139]
	global_store_dwordx4 v[138:139], v[130:133], off sc0 sc1
	global_store_dwordx4 v[138:139], v[134:137], off offset:16 sc0 sc1
.LBB0_225:
	s_andn2_saveexec_b64 s[2:3], s[2:3]
	s_cbranch_execz .LBB0_227
	v_add_u32_e32 v130, 0x90, v174
	v_and_b32_e32 v130, 0x7df, v130
	v_mov_b32_e32 v131, v143
	v_lshl_add_u64 v[130:131], v[176:177], 0, v[130:131]
	v_lshlrev_b64 v[130:131], 10, v[130:131]
	v_lshl_add_u64 v[130:131], s[28:29], 0, v[130:131]
	v_lshl_add_u64 v[130:131], v[142:143], 1, v[130:131]
	global_store_dwordx4 v[130:131], v[138:141], off sc0 sc1
.LBB0_227:
	s_or_b64 exec, exec, s[0:1]
	v_mul_hi_i32_i24_e32 v179, 30, v175
	v_mul_i32_i24_e32 v178, 30, v175
	v_cmp_gt_i32_e32 vcc, s71, v174
	s_and_saveexec_b64 s[0:1], vcc
	s_cbranch_execz .LBB0_232
	v_mul_f32_e32 v131, 0xbfb8aa3b, v22
	v_mul_f32_e32 v132, 0xbfb8aa3b, v19
	v_exp_f32_e32 v131, v131
	v_exp_f32_e32 v133, v132
	v_mul_f32_e32 v132, 0xbfb8aa3b, v23
	v_exp_f32_e32 v134, v132
	v_add_f32_e32 v131, 1.0, v131
	v_rcp_f32_e32 v132, v131
	v_add_f32_e32 v131, 1.0, v133
	v_add_f32_e32 v133, 1.0, v134
	v_mul_f32_e32 v134, 0xbfb8aa3b, v20
	v_exp_f32_e32 v134, v134
	v_mul_f32_e32 v135, 0xbfb8aa3b, v24
	v_exp_f32_e32 v135, v135
	v_mul_f32_e32 v130, 0xbfb8aa3b, v18
	v_add_f32_e32 v134, 1.0, v134
	v_rcp_f32_e32 v136, v134
	v_add_f32_e32 v134, 1.0, v135
	v_mul_f32_e32 v135, 0xbfb8aa3b, v21
	v_exp_f32_e32 v135, v135
	v_mul_f32_e32 v137, 0xbfb8aa3b, v25
	v_exp_f32_e32 v130, v130
	v_exp_f32_e32 v139, v137
	v_rcp_f32_e32 v138, v134
	v_add_f32_e32 v134, 1.0, v135
	v_add_f32_e32 v130, 1.0, v130
	v_rcp_f32_e32 v137, v134
	v_add_f32_e32 v134, 1.0, v139
	v_rcp_f32_e32 v130, v130
	v_rcp_f32_e32 v131, v131
	v_rcp_f32_e32 v133, v133
	v_rcp_f32_e32 v139, v134
	s_movk_i32 s2, 0x1f5f
	v_pk_mul_f32 v[134:135], v[26:27], v[130:131]
	v_pk_mul_f32 v[130:131], v[30:31], v[132:133]
	v_pk_mul_f32 v[136:137], v[28:29], v[136:137]
	v_pk_mul_f32 v[132:133], v[32:33], v[138:139]
	v_cmp_lt_i32_e32 vcc, s2, v174
	s_mov_b64 s[2:3], 0
	v_cvt_pk_bf16_f32 v138, v134, v135
	v_cvt_pk_bf16_f32 v139, v136, v137
	v_cvt_pk_bf16_f32 v140, v130, v131
	v_cvt_pk_bf16_f32 v141, v132, v133
	s_and_saveexec_b64 s[8:9], vcc
	s_xor_b64 s[8:9], exec, s[8:9]
	s_cbranch_execz .LBB0_353
	v_add_u32_e32 v175, 0xffffe0a0, v174
	v_lshrrev_b32_e32 v175, 2, v175
	v_mad_u64_u32 v[180:181], s[2:3], v175, 34, v[156:157]
	v_lshlrev_b64 v[180:181], 10, v[180:181]
	v_lshl_add_u64 v[180:181], s[34:35], 0, v[180:181]
	v_lshl_add_u64 v[180:181], v[142:143], 1, v[180:181]
	global_store_dwordx4 v[180:181], v[138:141], off sc0 sc1
	v_mad_u64_u32 v[180:181], s[2:3], v175, 30, v[158:159]
	s_mov_b64 s[2:3], exec
	s_or_saveexec_b64 s[8:9], s[8:9]
	v_mov_b64_e32 v[182:183], 0xa13c000
	s_xor_b64 exec, exec, s[8:9]
	s_cbranch_execnz .LBB0_354

.LBB0_231:
	v_readlane_b32 s2, v248, 38
	v_readlane_b32 s3, v248, 39
	s_load_dwordx16 s[52:67], s[2:3], 0x40
	v_lshlrev_b64 v[140:141], 11, v[180:181]
	s_waitcnt lgkmcnt(0)
	v_readlane_b32 s52, v248, 38
	v_readlane_b32 s53, v248, 39
	v_lshl_add_u64 v[138:139], s[66:67], 0, v[182:183]
	v_lshl_add_u64 v[138:139], v[138:139], 0, v[140:141]
	v_lshl_add_u64 v[138:139], v[142:143], 2, v[138:139]
	global_store_dwordx4 v[138:139], v[134:137], off sc0 sc1
	global_store_dwordx4 v[138:139], v[130:133], off offset:16 sc0 sc1
.LBB0_232:
	s_or_b64 exec, exec, s[0:1]
	v_cmp_gt_i32_e32 vcc, s4, v174
	s_and_saveexec_b64 s[0:1], vcc
	s_cbranch_execz .LBB0_237
	v_mul_f32_e32 v131, 0xbfb8aa3b, v6
	v_mul_f32_e32 v132, 0xbfb8aa3b, v3
	v_exp_f32_e32 v131, v131
	v_exp_f32_e32 v133, v132
	v_mul_f32_e32 v132, 0xbfb8aa3b, v7
	v_exp_f32_e32 v134, v132
	v_add_f32_e32 v131, 1.0, v131
	v_rcp_f32_e32 v132, v131
	v_add_f32_e32 v131, 1.0, v133
	v_add_f32_e32 v133, 1.0, v134
	v_mul_f32_e32 v134, 0xbfb8aa3b, v4
	v_exp_f32_e32 v134, v134
	v_mul_f32_e32 v135, 0xbfb8aa3b, v8
	v_exp_f32_e32 v135, v135
	v_mul_f32_e32 v130, 0xbfb8aa3b, v2
	v_add_f32_e32 v134, 1.0, v134
	v_rcp_f32_e32 v136, v134
	v_add_f32_e32 v134, 1.0, v135
	v_mul_f32_e32 v135, 0xbfb8aa3b, v5
	v_exp_f32_e32 v135, v135
	v_mul_f32_e32 v137, 0xbfb8aa3b, v9
	v_exp_f32_e32 v130, v130
	v_exp_f32_e32 v139, v137
	v_rcp_f32_e32 v138, v134
	v_add_f32_e32 v134, 1.0, v135
	v_add_f32_e32 v130, 1.0, v130
	v_rcp_f32_e32 v137, v134
	v_add_f32_e32 v134, 1.0, v139
	v_rcp_f32_e32 v130, v130
	v_rcp_f32_e32 v131, v131
	v_rcp_f32_e32 v133, v133
	v_rcp_f32_e32 v139, v134
	s_movk_i32 s2, 0x1f4f
	v_pk_mul_f32 v[134:135], v[10:11], v[130:131]
	v_pk_mul_f32 v[130:131], v[14:15], v[132:133]
	v_pk_mul_f32 v[136:137], v[12:13], v[136:137]
	v_pk_mul_f32 v[132:133], v[16:17], v[138:139]
	v_cmp_lt_i32_e32 vcc, s2, v174
	s_mov_b64 s[2:3], 0
	v_cvt_pk_bf16_f32 v138, v134, v135
	v_cvt_pk_bf16_f32 v139, v136, v137
	v_cvt_pk_bf16_f32 v140, v130, v131
	v_cvt_pk_bf16_f32 v141, v132, v133
	s_and_saveexec_b64 s[8:9], vcc
	s_xor_b64 s[8:9], exec, s[8:9]
	s_cbranch_execz .LBB0_357
	v_add_u32_e32 v175, 0xffffe0b0, v174
	v_lshrrev_b32_e32 v175, 2, v175
	v_mad_u64_u32 v[176:177], s[2:3], v175, 34, v[156:157]
	v_lshlrev_b64 v[176:177], 10, v[176:177]
	v_lshl_add_u64 v[176:177], s[34:35], 0, v[176:177]
	v_mad_u64_u32 v[180:181], s[2:3], v175, 30, v[158:159]
	v_lshl_add_u64 v[176:177], v[142:143], 1, v[176:177]
	s_mov_b64 s[2:3], exec
	global_store_dwordx4 v[176:177], v[138:141], off sc0 sc1
	s_or_saveexec_b64 s[8:9], s[8:9]
	v_mov_b64_e32 v[182:183], 0xa13c000
	s_xor_b64 exec, exec, s[8:9]
	s_cbranch_execnz .LBB0_358

.LBB0_247:
	v_mov_b64_e32 v[122:123], s[24:25]
	v_mad_i64_i32 v[122:123], s[2:3], v174, s92, v[122:123]
	v_lshl_add_u64 v[122:123], s[80:81], 1, v[122:123]
	v_lshlrev_b32_e32 v142, 1, v154
	v_lshl_add_u64 v[122:123], v[122:123], 0, v[142:143]
	s_and_b64 vcc, exec, s[10:11]
	v_cvt_pk_bf16_f32 v132, v132, v133
	v_cvt_pk_bf16_f32 v133, v124, v125
	v_cvt_pk_bf16_f32 v134, v126, v127
	v_cvt_pk_bf16_f32 v135, v128, v129
	global_store_dwordx4 v[122:123], v[132:135], off sc0 sc1
	s_cbranch_vccnz .LBB0_249
	global_store_dwordx4 v[130:131], v[114:117], off offset:512 nt
	global_store_dwordx4 v[130:131], v[118:121], off offset:528 nt

.LBB0_251:
	v_cvt_pk_bf16_f32 v114, v114, v115
	v_cvt_pk_bf16_f32 v115, v116, v117
	v_cvt_pk_bf16_f32 v116, v118, v119
	s_nop 0
	v_cvt_pk_bf16_f32 v117, v120, v121
	global_store_dwordx4 v[122:123], v[114:117], off offset:256 sc0 sc1

.LBB0_259:
	v_mov_b64_e32 v[106:107], s[24:25]
	v_mad_i64_i32 v[106:107], s[2:3], v118, s92, v[106:107]
	v_lshl_add_u64 v[106:107], s[80:81], 1, v[106:107]
	v_lshlrev_b32_e32 v142, 1, v154
	v_lshl_add_u64 v[106:107], v[106:107], 0, v[142:143]
	s_and_b64 vcc, exec, s[10:11]
	v_cvt_pk_bf16_f32 v116, v116, v117
	v_cvt_pk_bf16_f32 v117, v108, v109
	v_cvt_pk_bf16_f32 v118, v110, v111
	v_cvt_pk_bf16_f32 v119, v112, v113
	global_store_dwordx4 v[106:107], v[116:119], off sc0 sc1
	s_cbranch_vccnz .LBB0_261
	global_store_dwordx4 v[114:115], v[98:101], off offset:512 nt
	global_store_dwordx4 v[114:115], v[102:105], off offset:528 nt

.LBB0_263:
	v_cvt_pk_bf16_f32 v98, v98, v99
	v_cvt_pk_bf16_f32 v99, v100, v101
	v_cvt_pk_bf16_f32 v100, v102, v103
	s_nop 0
	v_cvt_pk_bf16_f32 v101, v104, v105
	global_store_dwordx4 v[106:107], v[98:101], off offset:256 sc0 sc1

.LBB0_271:
	v_mov_b64_e32 v[90:91], s[24:25]
	v_mad_i64_i32 v[90:91], s[2:3], v102, s92, v[90:91]
	v_lshl_add_u64 v[90:91], s[80:81], 1, v[90:91]
	v_lshlrev_b32_e32 v142, 1, v154
	v_lshl_add_u64 v[90:91], v[90:91], 0, v[142:143]
	s_and_b64 vcc, exec, s[10:11]
	v_cvt_pk_bf16_f32 v100, v100, v101
	v_cvt_pk_bf16_f32 v101, v92, v93
	v_cvt_pk_bf16_f32 v102, v94, v95
	v_cvt_pk_bf16_f32 v103, v96, v97
	global_store_dwordx4 v[90:91], v[100:103], off sc0 sc1
	s_cbranch_vccnz .LBB0_273
	global_store_dwordx4 v[98:99], v[82:85], off offset:512 nt
	global_store_dwordx4 v[98:99], v[86:89], off offset:528 nt

.LBB0_275:
	v_cvt_pk_bf16_f32 v82, v82, v83
	v_cvt_pk_bf16_f32 v83, v84, v85
	v_cvt_pk_bf16_f32 v84, v86, v87
	s_nop 0
	v_cvt_pk_bf16_f32 v85, v88, v89
	global_store_dwordx4 v[90:91], v[82:85], off offset:256 sc0 sc1

.LBB0_283:
	v_mov_b64_e32 v[74:75], s[24:25]
	v_mad_i64_i32 v[74:75], s[2:3], v86, s92, v[74:75]
	v_lshl_add_u64 v[74:75], s[80:81], 1, v[74:75]
	v_lshlrev_b32_e32 v142, 1, v154
	v_lshl_add_u64 v[74:75], v[74:75], 0, v[142:143]
	s_and_b64 vcc, exec, s[10:11]
	v_cvt_pk_bf16_f32 v84, v84, v85
	v_cvt_pk_bf16_f32 v85, v76, v77
	v_cvt_pk_bf16_f32 v86, v78, v79
	v_cvt_pk_bf16_f32 v87, v80, v81
	global_store_dwordx4 v[74:75], v[84:87], off sc0 sc1
	s_cbranch_vccnz .LBB0_285
	global_store_dwordx4 v[82:83], v[66:69], off offset:512 nt
	global_store_dwordx4 v[82:83], v[70:73], off offset:528 nt

.LBB0_287:
	v_cvt_pk_bf16_f32 v66, v66, v67
	v_cvt_pk_bf16_f32 v67, v68, v69
	v_cvt_pk_bf16_f32 v68, v70, v71
	s_nop 0
	v_cvt_pk_bf16_f32 v69, v72, v73
	global_store_dwordx4 v[74:75], v[66:69], off offset:256 sc0 sc1
	s_or_b64 exec, exec, s[0:1]
	v_cmp_gt_i32_e32 vcc, s41, v174
	s_and_saveexec_b64 s[0:1], vcc
	s_cbranch_execnz .LBB0_302

.LBB0_295:
	v_mov_b64_e32 v[42:43], s[24:25]
	v_mad_i64_i32 v[42:43], s[2:3], v54, s92, v[42:43]
	v_lshl_add_u64 v[42:43], s[80:81], 1, v[42:43]
	v_lshlrev_b32_e32 v142, 1, v154
	v_lshl_add_u64 v[42:43], v[42:43], 0, v[142:143]
	s_and_b64 vcc, exec, s[10:11]
	v_cvt_pk_bf16_f32 v52, v52, v53
	v_cvt_pk_bf16_f32 v53, v44, v45
	v_cvt_pk_bf16_f32 v54, v46, v47
	v_cvt_pk_bf16_f32 v55, v48, v49
	global_store_dwordx4 v[42:43], v[52:55], off sc0 sc1
	s_cbranch_vccnz .LBB0_297
	global_store_dwordx4 v[50:51], v[34:37], off offset:512 nt
	global_store_dwordx4 v[50:51], v[38:41], off offset:528 nt

.LBB0_299:
	v_cvt_pk_bf16_f32 v34, v34, v35
	v_cvt_pk_bf16_f32 v35, v36, v37
	v_cvt_pk_bf16_f32 v36, v38, v39
	s_nop 0
	v_cvt_pk_bf16_f32 v37, v40, v41
	global_store_dwordx4 v[42:43], v[34:37], off offset:256 sc0 sc1
	s_or_b64 exec, exec, s[0:1]
	v_cmp_gt_i32_e32 vcc, s71, v174
	s_and_saveexec_b64 s[0:1], vcc
	s_cbranch_execnz .LBB0_314

.LBB0_308:
	v_mov_b64_e32 v[58:59], s[24:25]
	v_mad_i64_i32 v[58:59], s[2:3], v70, s92, v[58:59]
	v_lshl_add_u64 v[58:59], s[80:81], 1, v[58:59]
	v_lshlrev_b32_e32 v142, 1, v154
	v_lshl_add_u64 v[58:59], v[58:59], 0, v[142:143]
	s_and_b64 vcc, exec, s[10:11]
	v_cvt_pk_bf16_f32 v68, v68, v69
	v_cvt_pk_bf16_f32 v69, v60, v61
	v_cvt_pk_bf16_f32 v70, v62, v63
	v_cvt_pk_bf16_f32 v71, v64, v65
	global_store_dwordx4 v[58:59], v[68:71], off sc0 sc1
	s_cbranch_vccnz .LBB0_310
	global_store_dwordx4 v[66:67], v[50:53], off offset:512 nt
	global_store_dwordx4 v[66:67], v[54:57], off offset:528 nt

.LBB0_312:
	v_cvt_pk_bf16_f32 v50, v50, v51
	v_cvt_pk_bf16_f32 v51, v52, v53
	v_cvt_pk_bf16_f32 v52, v54, v55
	s_nop 0
	v_cvt_pk_bf16_f32 v53, v56, v57
	global_store_dwordx4 v[58:59], v[50:53], off offset:256 sc0 sc1
	s_or_b64 exec, exec, s[0:1]
	v_cmp_gt_i32_e32 vcc, s87, v174
	s_and_saveexec_b64 s[0:1], vcc
	s_cbranch_execnz .LBB0_289

.LBB0_320:
	v_mov_b64_e32 v[26:27], s[24:25]
	v_mad_i64_i32 v[26:27], s[2:3], v38, s92, v[26:27]
	v_lshl_add_u64 v[26:27], s[80:81], 1, v[26:27]
	v_lshlrev_b32_e32 v142, 1, v154
	v_lshl_add_u64 v[26:27], v[26:27], 0, v[142:143]
	s_and_b64 vcc, exec, s[10:11]
	v_cvt_pk_bf16_f32 v36, v36, v37
	v_cvt_pk_bf16_f32 v37, v28, v29
	v_cvt_pk_bf16_f32 v38, v30, v31
	v_cvt_pk_bf16_f32 v39, v32, v33
	global_store_dwordx4 v[26:27], v[36:39], off sc0 sc1
	s_cbranch_vccnz .LBB0_322
	global_store_dwordx4 v[34:35], v[18:21], off offset:512 nt
	global_store_dwordx4 v[34:35], v[22:25], off offset:528 nt

.LBB0_324:
	v_cvt_pk_bf16_f32 v18, v18, v19
	v_cvt_pk_bf16_f32 v19, v20, v21
	v_cvt_pk_bf16_f32 v20, v22, v23
	s_nop 0
	v_cvt_pk_bf16_f32 v21, v24, v25
	global_store_dwordx4 v[26:27], v[18:21], off offset:256 sc0 sc1
	s_or_b64 exec, exec, s[0:1]
	v_cmp_gt_i32_e32 vcc, s4, v174
	s_and_saveexec_b64 s[0:1], vcc
	s_cbranch_execz .LBB0_336

.LBB0_331:
	v_mov_b64_e32 v[10:11], s[24:25]
	v_mad_i64_i32 v[10:11], s[2:3], v22, s92, v[10:11]
	v_lshl_add_u64 v[10:11], s[80:81], 1, v[10:11]
	v_lshlrev_b32_e32 v142, 1, v154
	v_lshl_add_u64 v[10:11], v[10:11], 0, v[142:143]
	s_and_b64 vcc, exec, s[10:11]
	v_cvt_pk_bf16_f32 v20, v20, v21
	v_cvt_pk_bf16_f32 v21, v12, v13
	v_cvt_pk_bf16_f32 v22, v14, v15
	v_cvt_pk_bf16_f32 v23, v16, v17
	global_store_dwordx4 v[10:11], v[20:23], off sc0 sc1
	s_cbranch_vccnz .LBB0_333
	global_store_dwordx4 v[18:19], v[2:5], off offset:512 nt
	global_store_dwordx4 v[18:19], v[6:9], off offset:528 nt

.LBB0_335:
	v_cvt_pk_bf16_f32 v2, v2, v3
	v_cvt_pk_bf16_f32 v3, v4, v5
	v_cvt_pk_bf16_f32 v4, v6, v7
	s_nop 0
	v_cvt_pk_bf16_f32 v5, v8, v9
	global_store_dwordx4 v[10:11], v[2:5], off offset:256 sc0 sc1

.LBB0_342:
	v_mul_f32_e32 v132, 0xbfb8aa3b, v58
	v_ashrrev_i32_e32 v175, 31, v174
	v_exp_f32_e32 v132, v132
	v_lshlrev_b64 v[130:131], 10, v[174:175]
	v_lshl_add_u64 v[130:131], s[26:27], 0, v[130:131]
	v_lshl_add_u64 v[130:131], s[42:43], 1, v[130:131]
	v_lshlrev_b32_e32 v142, 1, v154
	v_lshl_add_u64 v[134:135], v[130:131], 0, v[142:143]
	v_add_f32_e32 v130, 1.0, v132
	v_mul_f32_e32 v131, 0xbfb8aa3b, v62
	v_mul_f32_e32 v132, 0xbfb8aa3b, v59
	v_exp_f32_e32 v131, v131
	v_exp_f32_e32 v132, v132
	v_mul_f32_e32 v133, 0xbfb8aa3b, v63
	v_exp_f32_e32 v133, v133
	v_add_f32_e32 v131, 1.0, v131
	v_add_f32_e32 v132, 1.0, v132
	v_rcp_f32_e32 v131, v131
	v_rcp_f32_e32 v132, v132
	v_mul_f32_e32 v140, 0xbfb8aa3b, v61
	v_mul_f32_e32 v139, 0xbfb8aa3b, v64
	v_mul_f32_e32 v138, v62, v131
	v_mul_f32_e32 v131, v59, v132
	v_add_f32_e32 v132, 1.0, v133
	v_mul_f32_e32 v133, 0xbfb8aa3b, v60
	v_exp_f32_e32 v133, v133
	v_exp_f32_e32 v140, v140
	v_mul_f32_e32 v141, 0xbfb8aa3b, v65
	v_exp_f32_e32 v139, v139
	v_exp_f32_e32 v141, v141
	v_rcp_f32_e32 v130, v130
	v_rcp_f32_e32 v132, v132
	v_add_f32_e32 v133, 1.0, v133
	v_add_f32_e32 v140, 1.0, v140
	v_rcp_f32_e32 v133, v133
	v_add_f32_e32 v139, 1.0, v139
	v_rcp_f32_e32 v140, v140
	v_add_f32_e32 v141, 1.0, v141
	v_rcp_f32_e32 v139, v139
	v_rcp_f32_e32 v141, v141
	s_mov_b32 s3, 0x20000
	v_lshl_add_u64 v[136:137], v[134:135], 0, s[96:97]
	v_mul_f32_e32 v130, v58, v130
	v_mul_f32_e32 v132, v63, v132
	v_add_co_u32_e32 v134, vcc, s3, v134
	v_mul_f32_e32 v133, v60, v133
	v_mul_f32_e32 v140, v61, v140
	v_cvt_pk_bf16_f32 v130, v130, v131
	v_cvt_pk_bf16_f32 v131, v133, v140
	v_cvt_pk_bf16_f32 v132, v138, v132
	v_addc_co_u32_e32 v135, vcc, 0, v135, vcc
	v_mul_f32_e32 v139, v64, v139
	v_mul_f32_e32 v141, v65, v141
	v_cvt_pk_bf16_f32 v133, v139, v141
	global_store_dwordx4 v[134:135], v[130:133], off sc0 sc1
	v_mul_f32_e32 v138, 0xbfb8aa3b, v50
	v_exp_f32_e32 v138, v138
	v_mul_f32_e32 v131, 0xbfb8aa3b, v54
	v_mul_f32_e32 v132, 0xbfb8aa3b, v51
	v_exp_f32_e32 v131, v131
	v_exp_f32_e32 v132, v132
	v_mul_f32_e32 v133, 0xbfb8aa3b, v55
	v_exp_f32_e32 v133, v133
	v_add_f32_e32 v131, 1.0, v131
	v_add_f32_e32 v132, 1.0, v132
	v_rcp_f32_e32 v131, v131
	v_rcp_f32_e32 v132, v132
	v_add_f32_e32 v130, 1.0, v138
	v_mul_f32_e32 v135, 0xbfb8aa3b, v56
	v_mul_f32_e32 v134, v54, v131
	v_mul_f32_e32 v131, v51, v132
	v_add_f32_e32 v132, 1.0, v133
	v_mul_f32_e32 v133, 0xbfb8aa3b, v52
	v_exp_f32_e32 v133, v133
	v_mul_f32_e32 v138, 0xbfb8aa3b, v53
	v_mul_f32_e32 v139, 0xbfb8aa3b, v57
	v_exp_f32_e32 v135, v135
	v_exp_f32_e32 v138, v138
	v_exp_f32_e32 v139, v139
	v_add_f32_e32 v133, 1.0, v133
	v_rcp_f32_e32 v130, v130
	v_rcp_f32_e32 v132, v132
	v_rcp_f32_e32 v133, v133
	v_add_f32_e32 v135, 1.0, v135
	v_add_f32_e32 v138, 1.0, v138
	v_add_f32_e32 v139, 1.0, v139
	v_rcp_f32_e32 v135, v135
	v_rcp_f32_e32 v138, v138
	v_rcp_f32_e32 v139, v139
	v_mul_f32_e32 v130, v50, v130
	v_mul_f32_e32 v132, v55, v132
	v_mul_f32_e32 v133, v52, v133
	v_mul_f32_e32 v135, v56, v135
	v_mul_f32_e32 v138, v53, v138
	v_mul_f32_e32 v139, v57, v139
	v_cvt_pk_bf16_f32 v130, v130, v131
	v_cvt_pk_bf16_f32 v131, v133, v138
	v_cvt_pk_bf16_f32 v132, v134, v132
	v_cvt_pk_bf16_f32 v133, v135, v139
	global_store_dwordx4 v[136:137], v[130:133], off offset:256 sc0 sc1
	s_or_b64 exec, exec, s[0:1]
	v_cmp_gt_i32_e32 vcc, s87, v174
	s_and_saveexec_b64 s[0:1], vcc
	s_cbranch_execnz .LBB0_192

.LBB0_344:
	v_mul_f32_e32 v132, 0xbfb8aa3b, v26
	v_ashrrev_i32_e32 v175, 31, v174
	v_exp_f32_e32 v132, v132
	v_lshlrev_b64 v[130:131], 10, v[174:175]
	v_lshl_add_u64 v[130:131], s[26:27], 0, v[130:131]
	v_lshl_add_u64 v[130:131], s[42:43], 1, v[130:131]
	v_lshlrev_b32_e32 v142, 1, v154
	v_lshl_add_u64 v[134:135], v[130:131], 0, v[142:143]
	v_add_f32_e32 v130, 1.0, v132
	v_mul_f32_e32 v131, 0xbfb8aa3b, v30
	v_mul_f32_e32 v132, 0xbfb8aa3b, v27
	v_exp_f32_e32 v131, v131
	v_exp_f32_e32 v132, v132
	v_mul_f32_e32 v133, 0xbfb8aa3b, v31
	v_exp_f32_e32 v133, v133
	v_add_f32_e32 v131, 1.0, v131
	v_add_f32_e32 v132, 1.0, v132
	v_rcp_f32_e32 v131, v131
	v_rcp_f32_e32 v132, v132
	v_mul_f32_e32 v140, 0xbfb8aa3b, v29
	v_mul_f32_e32 v139, 0xbfb8aa3b, v32
	v_mul_f32_e32 v138, v30, v131
	v_mul_f32_e32 v131, v27, v132
	v_add_f32_e32 v132, 1.0, v133
	v_mul_f32_e32 v133, 0xbfb8aa3b, v28
	v_exp_f32_e32 v133, v133
	v_exp_f32_e32 v140, v140
	v_mul_f32_e32 v141, 0xbfb8aa3b, v33
	v_exp_f32_e32 v139, v139
	v_exp_f32_e32 v141, v141
	v_rcp_f32_e32 v130, v130
	v_rcp_f32_e32 v132, v132
	v_add_f32_e32 v133, 1.0, v133
	v_add_f32_e32 v140, 1.0, v140
	v_rcp_f32_e32 v133, v133
	v_add_f32_e32 v139, 1.0, v139
	v_rcp_f32_e32 v140, v140
	v_add_f32_e32 v141, 1.0, v141
	v_rcp_f32_e32 v139, v139
	v_rcp_f32_e32 v141, v141
	s_mov_b32 s3, 0x28000
	v_lshl_add_u64 v[136:137], v[134:135], 0, s[90:91]
	v_mul_f32_e32 v130, v26, v130
	v_mul_f32_e32 v132, v31, v132
	v_add_co_u32_e32 v134, vcc, s3, v134
	v_mul_f32_e32 v133, v28, v133
	v_mul_f32_e32 v140, v29, v140
	v_cvt_pk_bf16_f32 v130, v130, v131
	v_cvt_pk_bf16_f32 v131, v133, v140
	v_cvt_pk_bf16_f32 v132, v138, v132
	v_addc_co_u32_e32 v135, vcc, 0, v135, vcc
	v_mul_f32_e32 v139, v32, v139
	v_mul_f32_e32 v141, v33, v141
	v_cvt_pk_bf16_f32 v133, v139, v141
	global_store_dwordx4 v[134:135], v[130:133], off sc0 sc1
	v_mul_f32_e32 v138, 0xbfb8aa3b, v18
	v_exp_f32_e32 v138, v138
	v_mul_f32_e32 v131, 0xbfb8aa3b, v22
	v_mul_f32_e32 v132, 0xbfb8aa3b, v19
	v_exp_f32_e32 v131, v131
	v_exp_f32_e32 v132, v132
	v_mul_f32_e32 v133, 0xbfb8aa3b, v23
	v_exp_f32_e32 v133, v133
	v_add_f32_e32 v131, 1.0, v131
	v_add_f32_e32 v132, 1.0, v132
	v_rcp_f32_e32 v131, v131
	v_rcp_f32_e32 v132, v132
	v_add_f32_e32 v130, 1.0, v138
	v_mul_f32_e32 v135, 0xbfb8aa3b, v24
	v_mul_f32_e32 v134, v22, v131
	v_mul_f32_e32 v131, v19, v132
	v_add_f32_e32 v132, 1.0, v133
	v_mul_f32_e32 v133, 0xbfb8aa3b, v20
	v_exp_f32_e32 v133, v133
	v_mul_f32_e32 v138, 0xbfb8aa3b, v21
	v_mul_f32_e32 v139, 0xbfb8aa3b, v25
	v_exp_f32_e32 v135, v135
	v_exp_f32_e32 v138, v138
	v_exp_f32_e32 v139, v139
	v_add_f32_e32 v133, 1.0, v133
	v_rcp_f32_e32 v130, v130
	v_rcp_f32_e32 v132, v132
	v_rcp_f32_e32 v133, v133
	v_add_f32_e32 v135, 1.0, v135
	v_add_f32_e32 v138, 1.0, v138
	v_add_f32_e32 v139, 1.0, v139
	v_rcp_f32_e32 v135, v135
	v_rcp_f32_e32 v138, v138
	v_rcp_f32_e32 v139, v139
	v_mul_f32_e32 v130, v18, v130
	v_mul_f32_e32 v132, v23, v132
	v_mul_f32_e32 v133, v20, v133
	v_mul_f32_e32 v135, v24, v135
	v_mul_f32_e32 v138, v21, v138
	v_mul_f32_e32 v139, v25, v139
	v_cvt_pk_bf16_f32 v130, v130, v131
	v_cvt_pk_bf16_f32 v131, v133, v138
	v_cvt_pk_bf16_f32 v132, v134, v132
	v_cvt_pk_bf16_f32 v133, v135, v139
	global_store_dwordx4 v[136:137], v[130:133], off offset:256 sc0 sc1
	s_or_b64 exec, exec, s[0:1]
	v_cmp_gt_i32_e32 vcc, s4, v174
	s_and_saveexec_b64 s[0:1], vcc
	s_cbranch_execnz .LBB0_194
	s_branch .LBB0_195

.LBB0_346:
	v_and_b32_e32 v178, 0x7ef, v175
	v_mov_b32_e32 v179, v143
	v_lshl_add_u64 v[176:177], s[8:9], 0, v[178:179]
	v_lshlrev_b64 v[176:177], 10, v[176:177]
	v_lshl_add_u64 v[176:177], s[28:29], 0, v[176:177]
	s_movk_i32 s11, 0x7e1
	v_lshl_add_u64 v[176:177], v[142:143], 1, v[176:177]
	v_cmp_lt_u32_e32 vcc, s11, v178
	s_mov_b64 s[36:37], s[12:13]
	global_store_dwordx4 v[176:177], v[138:141], off sc0 sc1
	s_and_saveexec_b64 s[38:39], vcc
	s_nop 0
	v_add_u32_e32 v138, 0xfffff81e, v178
	v_mov_b32_e32 v139, v143
	v_lshl_add_u64 v[176:177], s[0:1], 0, v[138:139]
	s_or_b64 s[36:37], s[12:13], exec
	s_or_b64 exec, exec, s[38:39]
	s_andn2_b64 s[12:13], s[12:13], exec
	s_and_b64 s[36:37], s[36:37], exec
	v_mov_b64_e32 v[178:179], 0x4100000
	s_or_b64 s[12:13], s[12:13], s[36:37]
	s_or_b64 exec, exec, s[14:15]
	s_and_b64 exec, exec, s[12:13]
	s_cbranch_execnz .LBB0_211
	s_branch .LBB0_212

.LBB0_350:
	v_and_b32_e32 v178, 0x7ff, v175
	v_mov_b32_e32 v179, v143
	v_lshl_add_u64 v[176:177], s[8:9], 0, v[178:179]
	v_lshlrev_b64 v[176:177], 10, v[176:177]
	v_lshl_add_u64 v[176:177], s[28:29], 0, v[176:177]
	s_movk_i32 s8, 0x7e1
	v_lshl_add_u64 v[176:177], v[142:143], 1, v[176:177]
	v_cmp_lt_u32_e32 vcc, s8, v178
	s_mov_b64 s[8:9], s[12:13]
	global_store_dwordx4 v[176:177], v[138:141], off sc0 sc1
	s_and_saveexec_b64 s[36:37], vcc
	s_nop 0
	v_add_u32_e32 v138, 0xfffff81e, v178
	v_mov_b32_e32 v139, v143
	v_lshl_add_u64 v[176:177], s[0:1], 0, v[138:139]
	s_or_b64 s[8:9], s[12:13], exec
	s_or_b64 exec, exec, s[36:37]
	s_andn2_b64 s[0:1], s[12:13], exec
	s_and_b64 s[8:9], s[8:9], exec
	v_mov_b64_e32 v[178:179], 0x4100000
	s_or_b64 s[12:13], s[0:1], s[8:9]
	s_or_b64 exec, exec, s[14:15]
	s_and_b64 exec, exec, s[12:13]
	s_cbranch_execnz .LBB0_216
	s_branch .LBB0_217

.LBB0_354:
	v_add_u32_e32 v175, 0xa0, v174
	v_and_b32_e32 v182, 0x7ef, v175
	v_mov_b32_e32 v183, v143
	v_lshl_add_u64 v[180:181], v[176:177], 0, v[182:183]
	v_lshlrev_b64 v[180:181], 10, v[180:181]
	v_lshl_add_u64 v[180:181], s[28:29], 0, v[180:181]
	s_movk_i32 s11, 0x7e1
	v_lshl_add_u64 v[180:181], v[142:143], 1, v[180:181]
	v_cmp_lt_u32_e32 vcc, s11, v182
	s_mov_b64 s[12:13], s[2:3]
	global_store_dwordx4 v[180:181], v[138:141], off sc0 sc1
	s_and_saveexec_b64 s[14:15], vcc
	s_nop 0
	v_add_u32_e32 v138, 0xfffff81e, v182
	v_mov_b32_e32 v139, v143
	v_lshl_add_u64 v[180:181], v[178:179], 0, v[138:139]
	s_or_b64 s[12:13], s[2:3], exec
	s_or_b64 exec, exec, s[14:15]
	s_andn2_b64 s[2:3], s[2:3], exec
	s_and_b64 s[12:13], s[12:13], exec
	v_mov_b64_e32 v[182:183], 0x4100000
	s_or_b64 s[2:3], s[2:3], s[12:13]
	s_or_b64 exec, exec, s[8:9]
	s_and_b64 exec, exec, s[2:3]
	s_cbranch_execnz .LBB0_231
	s_branch .LBB0_232

.LBB0_358:
	v_add_u32_e32 v175, 0xb0, v174
	v_and_b32_e32 v182, 0x7ff, v175
	v_mov_b32_e32 v183, v143
	v_lshl_add_u64 v[176:177], v[176:177], 0, v[182:183]
	v_lshlrev_b64 v[176:177], 10, v[176:177]
	v_lshl_add_u64 v[176:177], s[28:29], 0, v[176:177]
	s_movk_i32 s11, 0x7e1
	v_lshl_add_u64 v[176:177], v[142:143], 1, v[176:177]
	v_cmp_lt_u32_e32 vcc, s11, v182
	s_mov_b64 s[12:13], s[2:3]
	global_store_dwordx4 v[176:177], v[138:141], off sc0 sc1
	s_and_saveexec_b64 s[14:15], vcc
	s_nop 0
	v_add_u32_e32 v138, 0xfffff81e, v182
	v_mov_b32_e32 v139, v143
	v_lshl_add_u64 v[180:181], v[178:179], 0, v[138:139]
	s_or_b64 s[12:13], s[2:3], exec
	s_or_b64 exec, exec, s[14:15]
	s_andn2_b64 s[2:3], s[2:3], exec
	s_and_b64 s[12:13], s[12:13], exec
	v_mov_b64_e32 v[182:183], 0x4100000
	s_or_b64 s[2:3], s[2:3], s[12:13]
	s_or_b64 exec, exec, s[8:9]
	s_and_b64 exec, exec, s[2:3]
	s_cbranch_execnz .LBB0_236
	s_branch .LBB0_237
